# v16 + s_setprio 1 moved in front of the barrier that opens each compute segment
# speedup vs baseline: 1.0062x; 1.0006x over previous
.LBB0_121:
	ds_read_b128 v[164:167], v131
	ds_read_b128 v[168:171], v131 offset:1024
	ds_read_b128 v[172:175], v131 offset:2048
	ds_read_b128 v[176:179], v131 offset:3072
	ds_read_b128 v[180:183], v160
	ds_read_b128 v[184:187], v160 offset:1024
	ds_read_b128 v[188:191], v160 offset:2048
	ds_read_b128 v[192:195], v160 offset:3072
	s_add_i32 s55, s52, 0xfffc0080
	s_cmp_eq_u32 s54, 12
	s_cselect_b32 s57, s16, s55
	s_cselect_b32 s56, s17, s53
	s_or_b32 s55, s57, 0x80
	s_mov_b32 m0, s40
	s_nop 0
	buffer_load_dwordx4 v156, s[12:15], s52 offen lds
	s_nop 0
	s_mov_b32 m0, s41
	s_nop 0
	buffer_load_dwordx4 v157, s[12:15], s52 offen lds
	ds_read_b128 v[196:199], v161
	ds_read_b128 v[200:203], v161 offset:1024
	ds_read_b128 v[204:207], v161 offset:2048
	ds_read_b128 v[208:211], v161 offset:3072
	ds_read_b128 v[212:215], v161 offset:4096
	ds_read_b128 v[216:219], v161 offset:5120
	ds_read_b128 v[220:223], v161 offset:6144
	ds_read_b128 v[224:227], v161 offset:7168
	s_waitcnt vmcnt(8)
	s_waitcnt lgkmcnt(0)
	s_setprio 1
	s_barrier
	v_mfma_f32_16x16x32_bf16 v[126:129], v[164:167], v[196:199], v[126:129]
	v_mfma_f32_16x16x32_bf16 v[122:125], v[172:175], v[196:199], v[122:125]
	v_mfma_f32_16x16x32_bf16 v[118:121], v[164:167], v[204:207], v[118:121]
	v_mfma_f32_16x16x32_bf16 v[110:113], v[172:175], v[204:207], v[110:113]
	v_mfma_f32_16x16x32_bf16 v[102:105], v[164:167], v[212:215], v[102:105]
	v_mfma_f32_16x16x32_bf16 v[94:97], v[172:175], v[212:215], v[94:97]
	v_mfma_f32_16x16x32_bf16 v[86:89], v[164:167], v[220:223], v[86:89]
	v_mfma_f32_16x16x32_bf16 v[78:81], v[172:175], v[220:223], v[78:81]
	v_mfma_f32_16x16x32_bf16 v[126:129], v[168:171], v[200:203], v[126:129]
	v_mfma_f32_16x16x32_bf16 v[122:125], v[176:179], v[200:203], v[122:125]
	v_mfma_f32_16x16x32_bf16 v[118:121], v[168:171], v[208:211], v[118:121]
	v_mfma_f32_16x16x32_bf16 v[110:113], v[176:179], v[208:211], v[110:113]
	v_mfma_f32_16x16x32_bf16 v[102:105], v[168:171], v[216:219], v[102:105]
	v_mfma_f32_16x16x32_bf16 v[94:97], v[176:179], v[216:219], v[94:97]
	v_mfma_f32_16x16x32_bf16 v[86:89], v[168:171], v[224:227], v[86:89]
	v_mfma_f32_16x16x32_bf16 v[78:81], v[176:179], v[224:227], v[78:81]
	s_setprio 0
	s_setprio 1
	v_mfma_f32_16x16x32_bf16 v[114:117], v[180:183], v[196:199], v[114:117]
	v_mfma_f32_16x16x32_bf16 v[106:109], v[188:191], v[196:199], v[106:109]
	v_mfma_f32_16x16x32_bf16 v[98:101], v[180:183], v[204:207], v[98:101]
	v_mfma_f32_16x16x32_bf16 v[90:93], v[188:191], v[204:207], v[90:93]
	v_mfma_f32_16x16x32_bf16 v[82:85], v[180:183], v[212:215], v[82:85]
	v_mfma_f32_16x16x32_bf16 v[74:77], v[188:191], v[212:215], v[74:77]
	v_mfma_f32_16x16x32_bf16 v[70:73], v[180:183], v[220:223], v[70:73]
	v_mfma_f32_16x16x32_bf16 v[66:69], v[188:191], v[220:223], v[66:69]
	v_mfma_f32_16x16x32_bf16 v[114:117], v[184:187], v[200:203], v[114:117]
	v_mfma_f32_16x16x32_bf16 v[106:109], v[192:195], v[200:203], v[106:109]
	v_mfma_f32_16x16x32_bf16 v[98:101], v[184:187], v[208:211], v[98:101]
	v_mfma_f32_16x16x32_bf16 v[90:93], v[192:195], v[208:211], v[90:93]
	v_mfma_f32_16x16x32_bf16 v[82:85], v[184:187], v[216:219], v[82:85]
	v_mfma_f32_16x16x32_bf16 v[74:77], v[192:195], v[216:219], v[74:77]
	v_mfma_f32_16x16x32_bf16 v[70:73], v[184:187], v[224:227], v[70:73]
	v_mfma_f32_16x16x32_bf16 v[66:69], v[192:195], v[224:227], v[66:69]
	s_barrier
	s_setprio 0
	ds_read_b128 v[196:199], v161 offset:16384
	ds_read_b128 v[200:203], v161 offset:17408
	s_mov_b32 m0, s22
	s_nop 0
	buffer_load_dwordx4 v154, s[8:11], s56 offen lds
	ds_read_b128 v[204:207], v161 offset:18432
	ds_read_b128 v[208:211], v161 offset:19456
	s_add_i32 s58, s56, 0x40000
	s_mov_b32 m0, s23
	s_nop 0
	buffer_load_dwordx4 v155, s[8:11], s56 offen lds
	ds_read_b128 v[212:215], v161 offset:20480
	ds_read_b128 v[216:219], v161 offset:21504
	s_nop 0
	s_mov_b32 m0, s24
	s_nop 0
	buffer_load_dwordx4 v154, s[8:11], s58 offen lds
	ds_read_b128 v[220:223], v161 offset:22528
	ds_read_b128 v[224:227], v161 offset:23552
	s_nop 0
	s_mov_b32 m0, s25
	s_nop 0
	buffer_load_dwordx4 v155, s[8:11], s58 offen lds
	s_nop 0
	s_mov_b32 m0, s21
	s_nop 0
	buffer_load_dwordx4 v156, s[12:15], s57 offen lds
	s_nop 0
	s_mov_b32 m0, s27
	s_nop 0
	buffer_load_dwordx4 v157, s[12:15], s57 offen lds
	s_waitcnt vmcnt(8)
	s_waitcnt lgkmcnt(0)
	s_setprio 1
	s_barrier
	v_mfma_f32_16x16x32_bf16 v[62:65], v[164:167], v[196:199], v[62:65]
	v_mfma_f32_16x16x32_bf16 v[58:61], v[172:175], v[196:199], v[58:61]
	v_mfma_f32_16x16x32_bf16 v[54:57], v[164:167], v[204:207], v[54:57]
	v_mfma_f32_16x16x32_bf16 v[46:49], v[172:175], v[204:207], v[46:49]
	v_mfma_f32_16x16x32_bf16 v[38:41], v[164:167], v[212:215], v[38:41]
	v_mfma_f32_16x16x32_bf16 v[30:33], v[172:175], v[212:215], v[30:33]
	v_mfma_f32_16x16x32_bf16 v[22:25], v[164:167], v[220:223], v[22:25]
	v_mfma_f32_16x16x32_bf16 v[14:17], v[172:175], v[220:223], v[14:17]
	v_mfma_f32_16x16x32_bf16 v[62:65], v[168:171], v[200:203], v[62:65]
	v_mfma_f32_16x16x32_bf16 v[58:61], v[176:179], v[200:203], v[58:61]
	v_mfma_f32_16x16x32_bf16 v[54:57], v[168:171], v[208:211], v[54:57]
	v_mfma_f32_16x16x32_bf16 v[46:49], v[176:179], v[208:211], v[46:49]
	v_mfma_f32_16x16x32_bf16 v[38:41], v[168:171], v[216:219], v[38:41]
	v_mfma_f32_16x16x32_bf16 v[30:33], v[176:179], v[216:219], v[30:33]
	v_mfma_f32_16x16x32_bf16 v[22:25], v[168:171], v[224:227], v[22:25]
	v_mfma_f32_16x16x32_bf16 v[14:17], v[176:179], v[224:227], v[14:17]
	s_setprio 0
	s_setprio 1
	v_mfma_f32_16x16x32_bf16 v[50:53], v[180:183], v[196:199], v[50:53]
	v_mfma_f32_16x16x32_bf16 v[42:45], v[188:191], v[196:199], v[42:45]
	v_mfma_f32_16x16x32_bf16 v[34:37], v[180:183], v[204:207], v[34:37]
	v_mfma_f32_16x16x32_bf16 v[26:29], v[188:191], v[204:207], v[26:29]
	v_mfma_f32_16x16x32_bf16 v[18:21], v[180:183], v[212:215], v[18:21]
	v_mfma_f32_16x16x32_bf16 v[10:13], v[188:191], v[212:215], v[10:13]
	v_mfma_f32_16x16x32_bf16 v[6:9], v[180:183], v[220:223], v[6:9]
	v_mfma_f32_16x16x32_bf16 v[2:5], v[188:191], v[220:223], v[2:5]
	v_mfma_f32_16x16x32_bf16 v[50:53], v[184:187], v[200:203], v[50:53]
	v_mfma_f32_16x16x32_bf16 v[42:45], v[192:195], v[200:203], v[42:45]
	v_mfma_f32_16x16x32_bf16 v[34:37], v[184:187], v[208:211], v[34:37]
	v_mfma_f32_16x16x32_bf16 v[26:29], v[192:195], v[208:211], v[26:29]
	v_mfma_f32_16x16x32_bf16 v[18:21], v[184:187], v[216:219], v[18:21]
	v_mfma_f32_16x16x32_bf16 v[10:13], v[192:195], v[216:219], v[10:13]
	v_mfma_f32_16x16x32_bf16 v[6:9], v[184:187], v[224:227], v[6:9]
	v_mfma_f32_16x16x32_bf16 v[2:5], v[192:195], v[224:227], v[2:5]
	s_barrier
	s_setprio 0
	ds_read_b128 v[164:167], v162
	ds_read_b128 v[168:171], v162 offset:1024
	ds_read_b128 v[172:175], v162 offset:2048
	ds_read_b128 v[176:179], v162 offset:3072
	ds_read_b128 v[180:183], v163
	ds_read_b128 v[184:187], v163 offset:1024
	ds_read_b128 v[188:191], v163 offset:2048
	ds_read_b128 v[192:195], v163 offset:3072
	s_add_i32 s57, s57, 0x40000
	s_mov_b32 m0, s28
	s_nop 0
	buffer_load_dwordx4 v156, s[12:15], s57 offen lds
	s_nop 0
	s_mov_b32 m0, s30
	s_nop 0
	buffer_load_dwordx4 v157, s[12:15], s57 offen lds
	ds_read_b128 v[196:199], v161 offset:32768
	ds_read_b128 v[200:203], v161 offset:33792
	ds_read_b128 v[204:207], v161 offset:34816
	ds_read_b128 v[208:211], v161 offset:35840
	ds_read_b128 v[212:215], v161 offset:36864
	ds_read_b128 v[216:219], v161 offset:37888
	ds_read_b128 v[220:223], v161 offset:38912
	ds_read_b128 v[224:227], v161 offset:39936
	s_waitcnt vmcnt(8)
	s_waitcnt lgkmcnt(0)
	s_setprio 1
	s_barrier
	v_mfma_f32_16x16x32_bf16 v[126:129], v[164:167], v[196:199], v[126:129]
	v_mfma_f32_16x16x32_bf16 v[122:125], v[172:175], v[196:199], v[122:125]
	v_mfma_f32_16x16x32_bf16 v[118:121], v[164:167], v[204:207], v[118:121]
	v_mfma_f32_16x16x32_bf16 v[110:113], v[172:175], v[204:207], v[110:113]
	v_mfma_f32_16x16x32_bf16 v[102:105], v[164:167], v[212:215], v[102:105]
	v_mfma_f32_16x16x32_bf16 v[94:97], v[172:175], v[212:215], v[94:97]
	v_mfma_f32_16x16x32_bf16 v[86:89], v[164:167], v[220:223], v[86:89]
	v_mfma_f32_16x16x32_bf16 v[78:81], v[172:175], v[220:223], v[78:81]
	v_mfma_f32_16x16x32_bf16 v[126:129], v[168:171], v[200:203], v[126:129]
	v_mfma_f32_16x16x32_bf16 v[122:125], v[176:179], v[200:203], v[122:125]
	v_mfma_f32_16x16x32_bf16 v[118:121], v[168:171], v[208:211], v[118:121]
	v_mfma_f32_16x16x32_bf16 v[110:113], v[176:179], v[208:211], v[110:113]
	v_mfma_f32_16x16x32_bf16 v[102:105], v[168:171], v[216:219], v[102:105]
	v_mfma_f32_16x16x32_bf16 v[94:97], v[176:179], v[216:219], v[94:97]
	v_mfma_f32_16x16x32_bf16 v[86:89], v[168:171], v[224:227], v[86:89]
	v_mfma_f32_16x16x32_bf16 v[78:81], v[176:179], v[224:227], v[78:81]
	s_setprio 0
	s_setprio 1
	v_mfma_f32_16x16x32_bf16 v[114:117], v[180:183], v[196:199], v[114:117]
	v_mfma_f32_16x16x32_bf16 v[106:109], v[188:191], v[196:199], v[106:109]
	v_mfma_f32_16x16x32_bf16 v[98:101], v[180:183], v[204:207], v[98:101]
	v_mfma_f32_16x16x32_bf16 v[90:93], v[188:191], v[204:207], v[90:93]
	v_mfma_f32_16x16x32_bf16 v[82:85], v[180:183], v[212:215], v[82:85]
	v_mfma_f32_16x16x32_bf16 v[74:77], v[188:191], v[212:215], v[74:77]
	v_mfma_f32_16x16x32_bf16 v[70:73], v[180:183], v[220:223], v[70:73]
	v_mfma_f32_16x16x32_bf16 v[66:69], v[188:191], v[220:223], v[66:69]
	v_mfma_f32_16x16x32_bf16 v[114:117], v[184:187], v[200:203], v[114:117]
	v_mfma_f32_16x16x32_bf16 v[106:109], v[192:195], v[200:203], v[106:109]
	v_mfma_f32_16x16x32_bf16 v[98:101], v[184:187], v[208:211], v[98:101]
	v_mfma_f32_16x16x32_bf16 v[90:93], v[192:195], v[208:211], v[90:93]
	v_mfma_f32_16x16x32_bf16 v[82:85], v[184:187], v[216:219], v[82:85]
	v_mfma_f32_16x16x32_bf16 v[74:77], v[192:195], v[216:219], v[74:77]
	v_mfma_f32_16x16x32_bf16 v[70:73], v[184:187], v[224:227], v[70:73]
	v_mfma_f32_16x16x32_bf16 v[66:69], v[192:195], v[224:227], v[66:69]
	s_barrier
	s_setprio 0
	ds_read_b128 v[196:199], v161 offset:49152
	ds_read_b128 v[200:203], v161 offset:50176
	s_or_b32 s57, s56, 0x80
	s_mov_b32 m0, s34
	s_nop 0
	buffer_load_dwordx4 v154, s[8:11], s57 offen lds
	ds_read_b128 v[204:207], v161 offset:51200
	ds_read_b128 v[208:211], v161 offset:52224
	s_add_i32 s56, s56, 0x40080
	s_mov_b32 m0, s35
	s_nop 0
	buffer_load_dwordx4 v155, s[8:11], s57 offen lds
	ds_read_b128 v[212:215], v161 offset:53248
	ds_read_b128 v[216:219], v161 offset:54272
	s_nop 0
	s_mov_b32 m0, s38
	s_nop 0
	buffer_load_dwordx4 v154, s[8:11], s56 offen lds
	ds_read_b128 v[220:223], v161 offset:55296
	ds_read_b128 v[224:227], v161 offset:56320
	s_nop 0
	s_mov_b32 m0, s39
	s_nop 0
	buffer_load_dwordx4 v155, s[8:11], s56 offen lds
	s_nop 0
	s_mov_b32 m0, s36
	s_nop 0
	buffer_load_dwordx4 v156, s[12:15], s55 offen lds
	s_nop 0
	s_mov_b32 m0, s37
	s_nop 0
	buffer_load_dwordx4 v157, s[12:15], s55 offen lds
	s_waitcnt vmcnt(8)
	s_waitcnt lgkmcnt(0)
	s_setprio 1
	s_barrier
	v_mfma_f32_16x16x32_bf16 v[62:65], v[164:167], v[196:199], v[62:65]
	v_mfma_f32_16x16x32_bf16 v[58:61], v[172:175], v[196:199], v[58:61]
	v_mfma_f32_16x16x32_bf16 v[54:57], v[164:167], v[204:207], v[54:57]
	v_mfma_f32_16x16x32_bf16 v[46:49], v[172:175], v[204:207], v[46:49]
	v_mfma_f32_16x16x32_bf16 v[38:41], v[164:167], v[212:215], v[38:41]
	v_mfma_f32_16x16x32_bf16 v[30:33], v[172:175], v[212:215], v[30:33]
	v_mfma_f32_16x16x32_bf16 v[22:25], v[164:167], v[220:223], v[22:25]
	v_mfma_f32_16x16x32_bf16 v[14:17], v[172:175], v[220:223], v[14:17]
	v_mfma_f32_16x16x32_bf16 v[62:65], v[168:171], v[200:203], v[62:65]
	v_mfma_f32_16x16x32_bf16 v[58:61], v[176:179], v[200:203], v[58:61]
	v_mfma_f32_16x16x32_bf16 v[54:57], v[168:171], v[208:211], v[54:57]
	v_mfma_f32_16x16x32_bf16 v[46:49], v[176:179], v[208:211], v[46:49]
	v_mfma_f32_16x16x32_bf16 v[38:41], v[168:171], v[216:219], v[38:41]
	v_mfma_f32_16x16x32_bf16 v[30:33], v[176:179], v[216:219], v[30:33]
	v_mfma_f32_16x16x32_bf16 v[22:25], v[168:171], v[224:227], v[22:25]
	v_mfma_f32_16x16x32_bf16 v[14:17], v[176:179], v[224:227], v[14:17]
	s_setprio 0
	s_setprio 1
	v_mfma_f32_16x16x32_bf16 v[50:53], v[180:183], v[196:199], v[50:53]
	v_mfma_f32_16x16x32_bf16 v[42:45], v[188:191], v[196:199], v[42:45]
	v_mfma_f32_16x16x32_bf16 v[34:37], v[180:183], v[204:207], v[34:37]
	v_mfma_f32_16x16x32_bf16 v[26:29], v[188:191], v[204:207], v[26:29]
	v_mfma_f32_16x16x32_bf16 v[18:21], v[180:183], v[212:215], v[18:21]
	v_mfma_f32_16x16x32_bf16 v[10:13], v[188:191], v[212:215], v[10:13]
	v_mfma_f32_16x16x32_bf16 v[6:9], v[180:183], v[220:223], v[6:9]
	v_mfma_f32_16x16x32_bf16 v[2:5], v[188:191], v[220:223], v[2:5]
	v_mfma_f32_16x16x32_bf16 v[50:53], v[184:187], v[200:203], v[50:53]
	v_mfma_f32_16x16x32_bf16 v[42:45], v[192:195], v[200:203], v[42:45]
	v_mfma_f32_16x16x32_bf16 v[34:37], v[184:187], v[208:211], v[34:37]
	v_mfma_f32_16x16x32_bf16 v[26:29], v[192:195], v[208:211], v[26:29]
	v_mfma_f32_16x16x32_bf16 v[18:21], v[184:187], v[216:219], v[18:21]
	v_mfma_f32_16x16x32_bf16 v[10:13], v[192:195], v[216:219], v[10:13]
	v_mfma_f32_16x16x32_bf16 v[6:9], v[184:187], v[224:227], v[6:9]
	v_mfma_f32_16x16x32_bf16 v[2:5], v[192:195], v[224:227], v[2:5]
	s_barrier
	s_setprio 0
	s_add_i32 s54, s54, 2
	s_addk_i32 s52, 0x100
	s_addk_i32 s53, 0x100
	s_cmp_gt_u32 s54, 13
	s_cbranch_scc0 .LBB0_121
	s_and_b64 vcc, exec, s[6:7]
	s_cbranch_vccz .LBB0_126
	s_barrier
	s_cmp_gt_i32 s46, 3
	s_mov_b64 s[16:17], -1
	s_cbranch_scc1 .LBB0_127

.LBB0_223:
	v_add_u32_e32 v150, 0x10000, v132
	v_add_u32_e32 v166, 0x14000, v132
	ds_read_b128 v[134:137], v150
	ds_read_b128 v[142:145], v150 offset:1024
	ds_read_b128 v[146:149], v150 offset:2048
	ds_read_b128 v[150:153], v150 offset:3072
	ds_read_b128 v[154:157], v166
	ds_read_b128 v[158:161], v166 offset:1024
	ds_read_b128 v[162:165], v166 offset:2048
	ds_read_b128 v[166:169], v166 offset:3072
	s_add_i32 s63, s39, s60
	s_add_i32 s62, s34, s60
	s_add_i32 s61, s63, 0x800
	s_addk_i32 s62, 0x800
	s_cmp_eq_u32 s60, 0
	s_cselect_b32 s64, s55, s61
	s_cselect_b32 s62, s58, s62
	s_or_b32 s61, s64, 0x80
	s_add_i32 s63, s63, 0x40780
	s_mov_b32 m0, s49
	s_nop 0
	buffer_load_dwordx4 v130, s[12:15], s63 offen lds
	s_nop 0
	s_mov_b32 m0, s50
	s_nop 0
	buffer_load_dwordx4 v131, s[12:15], s63 offen lds
	ds_read_b128 v[170:173], v133
	ds_read_b128 v[174:177], v133 offset:1024
	ds_read_b128 v[178:181], v133 offset:2048
	ds_read_b128 v[182:185], v133 offset:3072
	ds_read_b128 v[186:189], v133 offset:4096
	ds_read_b128 v[190:193], v133 offset:5120
	ds_read_b128 v[194:197], v133 offset:6144
	ds_read_b128 v[198:201], v133 offset:7168
	s_waitcnt vmcnt(8)
	s_waitcnt lgkmcnt(0)
	s_setprio 1
	s_barrier
	v_mfma_f32_16x16x32_bf16 v[138:141], v[134:137], v[170:173], v[138:141]
	v_mfma_f32_16x16x32_bf16 v[126:129], v[146:149], v[170:173], v[126:129]
	v_mfma_f32_16x16x32_bf16 v[110:113], v[134:137], v[178:181], v[110:113]
	v_mfma_f32_16x16x32_bf16 v[106:109], v[146:149], v[178:181], v[106:109]
	v_mfma_f32_16x16x32_bf16 v[94:97], v[134:137], v[186:189], v[94:97]
	v_mfma_f32_16x16x32_bf16 v[90:93], v[146:149], v[186:189], v[90:93]
	v_mfma_f32_16x16x32_bf16 v[78:81], v[134:137], v[194:197], v[78:81]
	v_mfma_f32_16x16x32_bf16 v[74:77], v[146:149], v[194:197], v[74:77]
	v_mfma_f32_16x16x32_bf16 v[138:141], v[142:145], v[174:177], v[138:141]
	v_mfma_f32_16x16x32_bf16 v[126:129], v[150:153], v[174:177], v[126:129]
	v_mfma_f32_16x16x32_bf16 v[110:113], v[142:145], v[182:185], v[110:113]
	v_mfma_f32_16x16x32_bf16 v[106:109], v[150:153], v[182:185], v[106:109]
	v_mfma_f32_16x16x32_bf16 v[94:97], v[142:145], v[190:193], v[94:97]
	v_mfma_f32_16x16x32_bf16 v[90:93], v[150:153], v[190:193], v[90:93]
	v_mfma_f32_16x16x32_bf16 v[78:81], v[142:145], v[198:201], v[78:81]
	v_mfma_f32_16x16x32_bf16 v[74:77], v[150:153], v[198:201], v[74:77]
	s_setprio 0
	s_setprio 1
	v_mfma_f32_16x16x32_bf16 v[118:121], v[154:157], v[170:173], v[118:121]
	v_mfma_f32_16x16x32_bf16 v[114:117], v[162:165], v[170:173], v[114:117]
	v_mfma_f32_16x16x32_bf16 v[102:105], v[154:157], v[178:181], v[102:105]
	v_mfma_f32_16x16x32_bf16 v[98:101], v[162:165], v[178:181], v[98:101]
	v_mfma_f32_16x16x32_bf16 v[86:89], v[154:157], v[186:189], v[86:89]
	v_mfma_f32_16x16x32_bf16 v[82:85], v[162:165], v[186:189], v[82:85]
	v_mfma_f32_16x16x32_bf16 v[70:73], v[154:157], v[194:197], v[70:73]
	v_mfma_f32_16x16x32_bf16 v[66:69], v[162:165], v[194:197], v[66:69]
	v_mfma_f32_16x16x32_bf16 v[118:121], v[158:161], v[174:177], v[118:121]
	v_mfma_f32_16x16x32_bf16 v[114:117], v[166:169], v[174:177], v[114:117]
	v_mfma_f32_16x16x32_bf16 v[102:105], v[158:161], v[182:185], v[102:105]
	v_mfma_f32_16x16x32_bf16 v[98:101], v[166:169], v[182:185], v[98:101]
	v_mfma_f32_16x16x32_bf16 v[86:89], v[158:161], v[190:193], v[86:89]
	v_mfma_f32_16x16x32_bf16 v[82:85], v[166:169], v[190:193], v[82:85]
	v_mfma_f32_16x16x32_bf16 v[70:73], v[158:161], v[198:201], v[70:73]
	v_mfma_f32_16x16x32_bf16 v[66:69], v[166:169], v[198:201], v[66:69]
	s_barrier
	s_setprio 0
	ds_read_b128 v[170:173], v133 offset:16384
	ds_read_b128 v[174:177], v133 offset:17408
	s_mov_b32 m0, s33
	s_nop 0
	buffer_load_dwordx4 v130, s[8:11], s62 offen lds
	ds_read_b128 v[178:181], v133 offset:18432
	ds_read_b128 v[182:185], v133 offset:19456
	s_add_i32 s63, s62, 0x40000
	s_mov_b32 m0, s35
	s_nop 0
	buffer_load_dwordx4 v131, s[8:11], s62 offen lds
	ds_read_b128 v[186:189], v133 offset:20480
	ds_read_b128 v[190:193], v133 offset:21504
	s_nop 0
	s_mov_b32 m0, s36
	s_nop 0
	buffer_load_dwordx4 v130, s[8:11], s63 offen lds
	ds_read_b128 v[194:197], v133 offset:22528
	ds_read_b128 v[198:201], v133 offset:23552
	s_nop 0
	s_mov_b32 m0, s37
	s_nop 0
	buffer_load_dwordx4 v131, s[8:11], s63 offen lds
	s_nop 0
	s_mov_b32 m0, s31
	s_nop 0
	buffer_load_dwordx4 v130, s[12:15], s64 offen lds
	s_nop 0
	s_mov_b32 m0, s40
	s_nop 0
	buffer_load_dwordx4 v131, s[12:15], s64 offen lds
	s_waitcnt vmcnt(8)
	s_waitcnt lgkmcnt(0)
	s_setprio 1
	s_barrier
	v_mfma_f32_16x16x32_bf16 v[62:65], v[134:137], v[170:173], v[62:65]
	v_mfma_f32_16x16x32_bf16 v[58:61], v[146:149], v[170:173], v[58:61]
	v_mfma_f32_16x16x32_bf16 v[46:49], v[134:137], v[178:181], v[46:49]
	v_mfma_f32_16x16x32_bf16 v[42:45], v[146:149], v[178:181], v[42:45]
	v_mfma_f32_16x16x32_bf16 v[30:33], v[134:137], v[186:189], v[30:33]
	v_mfma_f32_16x16x32_bf16 v[26:29], v[146:149], v[186:189], v[26:29]
	v_mfma_f32_16x16x32_bf16 v[14:17], v[134:137], v[194:197], v[14:17]
	v_mfma_f32_16x16x32_bf16 v[10:13], v[146:149], v[194:197], v[10:13]
	v_mfma_f32_16x16x32_bf16 v[62:65], v[142:145], v[174:177], v[62:65]
	v_mfma_f32_16x16x32_bf16 v[58:61], v[150:153], v[174:177], v[58:61]
	v_mfma_f32_16x16x32_bf16 v[46:49], v[142:145], v[182:185], v[46:49]
	v_mfma_f32_16x16x32_bf16 v[42:45], v[150:153], v[182:185], v[42:45]
	v_mfma_f32_16x16x32_bf16 v[30:33], v[142:145], v[190:193], v[30:33]
	v_mfma_f32_16x16x32_bf16 v[26:29], v[150:153], v[190:193], v[26:29]
	v_mfma_f32_16x16x32_bf16 v[14:17], v[142:145], v[198:201], v[14:17]
	v_mfma_f32_16x16x32_bf16 v[10:13], v[150:153], v[198:201], v[10:13]
	s_setprio 0
	s_setprio 1
	v_mfma_f32_16x16x32_bf16 v[54:57], v[154:157], v[170:173], v[54:57]
	v_mfma_f32_16x16x32_bf16 v[50:53], v[162:165], v[170:173], v[50:53]
	v_mfma_f32_16x16x32_bf16 v[38:41], v[154:157], v[178:181], v[38:41]
	v_mfma_f32_16x16x32_bf16 v[34:37], v[162:165], v[178:181], v[34:37]
	v_mfma_f32_16x16x32_bf16 v[22:25], v[154:157], v[186:189], v[22:25]
	v_mfma_f32_16x16x32_bf16 v[18:21], v[162:165], v[186:189], v[18:21]
	v_mfma_f32_16x16x32_bf16 v[6:9], v[154:157], v[194:197], v[6:9]
	v_mfma_f32_16x16x32_bf16 v[2:5], v[162:165], v[194:197], v[2:5]
	v_mfma_f32_16x16x32_bf16 v[54:57], v[158:161], v[174:177], v[54:57]
	v_mfma_f32_16x16x32_bf16 v[50:53], v[166:169], v[174:177], v[50:53]
	v_mfma_f32_16x16x32_bf16 v[38:41], v[158:161], v[182:185], v[38:41]
	v_mfma_f32_16x16x32_bf16 v[34:37], v[166:169], v[182:185], v[34:37]
	v_mfma_f32_16x16x32_bf16 v[22:25], v[158:161], v[190:193], v[22:25]
	v_mfma_f32_16x16x32_bf16 v[18:21], v[166:169], v[190:193], v[18:21]
	v_mfma_f32_16x16x32_bf16 v[6:9], v[158:161], v[198:201], v[6:9]
	v_mfma_f32_16x16x32_bf16 v[2:5], v[166:169], v[198:201], v[2:5]
	s_barrier
	s_setprio 0
	v_add_u32_e32 v150, 0x18000, v132
	v_add_u32_e32 v166, 0x1c000, v132
	ds_read_b128 v[134:137], v150
	ds_read_b128 v[142:145], v150 offset:1024
	ds_read_b128 v[146:149], v150 offset:2048
	ds_read_b128 v[150:153], v150 offset:3072
	ds_read_b128 v[154:157], v166
	ds_read_b128 v[158:161], v166 offset:1024
	ds_read_b128 v[162:165], v166 offset:2048
	ds_read_b128 v[166:169], v166 offset:3072
	s_add_i32 s63, s64, 0x40000
	s_mov_b32 m0, s41
	s_nop 0
	buffer_load_dwordx4 v130, s[12:15], s63 offen lds
	s_nop 0
	s_mov_b32 m0, s42
	s_nop 0
	buffer_load_dwordx4 v131, s[12:15], s63 offen lds
	ds_read_b128 v[170:173], v133 offset:32768
	ds_read_b128 v[174:177], v133 offset:33792
	ds_read_b128 v[178:181], v133 offset:34816
	ds_read_b128 v[182:185], v133 offset:35840
	ds_read_b128 v[186:189], v133 offset:36864
	ds_read_b128 v[190:193], v133 offset:37888
	ds_read_b128 v[194:197], v133 offset:38912
	ds_read_b128 v[198:201], v133 offset:39936
	s_waitcnt vmcnt(8)
	s_waitcnt lgkmcnt(0)
	s_setprio 1
	s_barrier
	v_mfma_f32_16x16x32_bf16 v[138:141], v[134:137], v[170:173], v[138:141]
	v_mfma_f32_16x16x32_bf16 v[126:129], v[146:149], v[170:173], v[126:129]
	v_mfma_f32_16x16x32_bf16 v[110:113], v[134:137], v[178:181], v[110:113]
	v_mfma_f32_16x16x32_bf16 v[106:109], v[146:149], v[178:181], v[106:109]
	v_mfma_f32_16x16x32_bf16 v[94:97], v[134:137], v[186:189], v[94:97]
	v_mfma_f32_16x16x32_bf16 v[90:93], v[146:149], v[186:189], v[90:93]
	v_mfma_f32_16x16x32_bf16 v[78:81], v[134:137], v[194:197], v[78:81]
	v_mfma_f32_16x16x32_bf16 v[74:77], v[146:149], v[194:197], v[74:77]
	v_mfma_f32_16x16x32_bf16 v[138:141], v[142:145], v[174:177], v[138:141]
	v_mfma_f32_16x16x32_bf16 v[126:129], v[150:153], v[174:177], v[126:129]
	v_mfma_f32_16x16x32_bf16 v[110:113], v[142:145], v[182:185], v[110:113]
	v_mfma_f32_16x16x32_bf16 v[106:109], v[150:153], v[182:185], v[106:109]
	v_mfma_f32_16x16x32_bf16 v[94:97], v[142:145], v[190:193], v[94:97]
	v_mfma_f32_16x16x32_bf16 v[90:93], v[150:153], v[190:193], v[90:93]
	v_mfma_f32_16x16x32_bf16 v[78:81], v[142:145], v[198:201], v[78:81]
	v_mfma_f32_16x16x32_bf16 v[74:77], v[150:153], v[198:201], v[74:77]
	s_setprio 0
	s_setprio 1
	v_mfma_f32_16x16x32_bf16 v[118:121], v[154:157], v[170:173], v[118:121]
	v_mfma_f32_16x16x32_bf16 v[114:117], v[162:165], v[170:173], v[114:117]
	v_mfma_f32_16x16x32_bf16 v[102:105], v[154:157], v[178:181], v[102:105]
	v_mfma_f32_16x16x32_bf16 v[98:101], v[162:165], v[178:181], v[98:101]
	v_mfma_f32_16x16x32_bf16 v[86:89], v[154:157], v[186:189], v[86:89]
	v_mfma_f32_16x16x32_bf16 v[82:85], v[162:165], v[186:189], v[82:85]
	v_mfma_f32_16x16x32_bf16 v[70:73], v[154:157], v[194:197], v[70:73]
	v_mfma_f32_16x16x32_bf16 v[66:69], v[162:165], v[194:197], v[66:69]
	v_mfma_f32_16x16x32_bf16 v[118:121], v[158:161], v[174:177], v[118:121]
	v_mfma_f32_16x16x32_bf16 v[114:117], v[166:169], v[174:177], v[114:117]
	v_mfma_f32_16x16x32_bf16 v[102:105], v[158:161], v[182:185], v[102:105]
	v_mfma_f32_16x16x32_bf16 v[98:101], v[166:169], v[182:185], v[98:101]
	v_mfma_f32_16x16x32_bf16 v[86:89], v[158:161], v[190:193], v[86:89]
	v_mfma_f32_16x16x32_bf16 v[82:85], v[166:169], v[190:193], v[82:85]
	v_mfma_f32_16x16x32_bf16 v[70:73], v[158:161], v[198:201], v[70:73]
	v_mfma_f32_16x16x32_bf16 v[66:69], v[166:169], v[198:201], v[66:69]
	s_barrier
	s_setprio 0
	ds_read_b128 v[170:173], v133 offset:49152
	ds_read_b128 v[174:177], v133 offset:50176
	s_or_b32 s63, s62, 0x80
	s_mov_b32 m0, s43
	s_nop 0
	buffer_load_dwordx4 v130, s[8:11], s63 offen lds
	ds_read_b128 v[178:181], v133 offset:51200
	ds_read_b128 v[182:185], v133 offset:52224
	s_add_i32 s62, s62, 0x40080
	s_mov_b32 m0, s44
	s_nop 0
	buffer_load_dwordx4 v131, s[8:11], s63 offen lds
	ds_read_b128 v[186:189], v133 offset:53248
	ds_read_b128 v[190:193], v133 offset:54272
	s_nop 0
	s_mov_b32 m0, s47
	s_nop 0
	buffer_load_dwordx4 v130, s[8:11], s62 offen lds
	ds_read_b128 v[194:197], v133 offset:55296
	ds_read_b128 v[198:201], v133 offset:56320
	s_nop 0
	s_mov_b32 m0, s48
	s_nop 0
	buffer_load_dwordx4 v131, s[8:11], s62 offen lds
	s_nop 0
	s_mov_b32 m0, s45
	s_nop 0
	buffer_load_dwordx4 v130, s[12:15], s61 offen lds
	s_nop 0
	s_mov_b32 m0, s46
	s_nop 0
	buffer_load_dwordx4 v131, s[12:15], s61 offen lds
	s_waitcnt vmcnt(8)
	s_waitcnt lgkmcnt(0)
	s_setprio 1
	s_barrier
	v_mfma_f32_16x16x32_bf16 v[62:65], v[134:137], v[170:173], v[62:65]
	v_mfma_f32_16x16x32_bf16 v[58:61], v[146:149], v[170:173], v[58:61]
	v_mfma_f32_16x16x32_bf16 v[46:49], v[134:137], v[178:181], v[46:49]
	v_mfma_f32_16x16x32_bf16 v[42:45], v[146:149], v[178:181], v[42:45]
	v_mfma_f32_16x16x32_bf16 v[30:33], v[134:137], v[186:189], v[30:33]
	v_mfma_f32_16x16x32_bf16 v[26:29], v[146:149], v[186:189], v[26:29]
	v_mfma_f32_16x16x32_bf16 v[14:17], v[134:137], v[194:197], v[14:17]
	v_mfma_f32_16x16x32_bf16 v[10:13], v[146:149], v[194:197], v[10:13]
	v_mfma_f32_16x16x32_bf16 v[62:65], v[142:145], v[174:177], v[62:65]
	v_mfma_f32_16x16x32_bf16 v[58:61], v[150:153], v[174:177], v[58:61]
	v_mfma_f32_16x16x32_bf16 v[46:49], v[142:145], v[182:185], v[46:49]
	v_mfma_f32_16x16x32_bf16 v[42:45], v[150:153], v[182:185], v[42:45]
	v_mfma_f32_16x16x32_bf16 v[30:33], v[142:145], v[190:193], v[30:33]
	v_mfma_f32_16x16x32_bf16 v[26:29], v[150:153], v[190:193], v[26:29]
	v_mfma_f32_16x16x32_bf16 v[14:17], v[142:145], v[198:201], v[14:17]
	v_mfma_f32_16x16x32_bf16 v[10:13], v[150:153], v[198:201], v[10:13]
	s_setprio 0
	s_setprio 1
	v_mfma_f32_16x16x32_bf16 v[54:57], v[154:157], v[170:173], v[54:57]
	v_mfma_f32_16x16x32_bf16 v[50:53], v[162:165], v[170:173], v[50:53]
	v_mfma_f32_16x16x32_bf16 v[38:41], v[154:157], v[178:181], v[38:41]
	v_mfma_f32_16x16x32_bf16 v[34:37], v[162:165], v[178:181], v[34:37]
	v_mfma_f32_16x16x32_bf16 v[22:25], v[154:157], v[186:189], v[22:25]
	v_mfma_f32_16x16x32_bf16 v[18:21], v[162:165], v[186:189], v[18:21]
	v_mfma_f32_16x16x32_bf16 v[6:9], v[154:157], v[194:197], v[6:9]
	v_mfma_f32_16x16x32_bf16 v[2:5], v[162:165], v[194:197], v[2:5]
	v_mfma_f32_16x16x32_bf16 v[54:57], v[158:161], v[174:177], v[54:57]
	v_mfma_f32_16x16x32_bf16 v[50:53], v[166:169], v[174:177], v[50:53]
	v_mfma_f32_16x16x32_bf16 v[38:41], v[158:161], v[182:185], v[38:41]
	v_mfma_f32_16x16x32_bf16 v[34:37], v[166:169], v[182:185], v[34:37]
	v_mfma_f32_16x16x32_bf16 v[22:25], v[158:161], v[190:193], v[22:25]
	v_mfma_f32_16x16x32_bf16 v[18:21], v[166:169], v[190:193], v[18:21]
	v_mfma_f32_16x16x32_bf16 v[6:9], v[158:161], v[198:201], v[6:9]
	v_mfma_f32_16x16x32_bf16 v[2:5], v[166:169], v[198:201], v[2:5]
	s_barrier
	s_setprio 0
	s_add_i32 s59, s59, 2
	s_addk_i32 s60, 0x100
	s_cmp_gt_u32 s59, 13
	s_cbranch_scc0 .LBB0_223
	s_andn2_b64 vcc, exec, s[6:7]
	s_cbranch_vccnz .LBB0_215
	v_mov_b32_e32 v2, 0
	s_mov_b32 s18, s52
	s_mov_b32 s29, s53
	s_mov_b32 s34, s3
	s_mov_b32 s39, s2
	s_mov_b32 s51, s54
	v_mov_b32_e32 v3, v2
	v_mov_b32_e32 v4, v2
	v_mov_b32_e32 v5, v2
	v_mov_b32_e32 v6, v2
	v_mov_b32_e32 v7, v2
	v_mov_b32_e32 v8, v2
	v_mov_b32_e32 v9, v2
	v_mov_b32_e32 v18, v2
	v_mov_b32_e32 v19, v2
	v_mov_b32_e32 v20, v2
	v_mov_b32_e32 v21, v2
	v_mov_b32_e32 v22, v2
	v_mov_b32_e32 v23, v2
	v_mov_b32_e32 v24, v2
	v_mov_b32_e32 v25, v2
	v_mov_b32_e32 v34, v2
	v_mov_b32_e32 v35, v2
	v_mov_b32_e32 v36, v2
	v_mov_b32_e32 v37, v2
	v_mov_b32_e32 v38, v2
	v_mov_b32_e32 v39, v2
	v_mov_b32_e32 v40, v2
	v_mov_b32_e32 v41, v2
	v_mov_b32_e32 v50, v2
	v_mov_b32_e32 v51, v2
	v_mov_b32_e32 v52, v2
	v_mov_b32_e32 v53, v2
	v_mov_b32_e32 v54, v2
	v_mov_b32_e32 v55, v2
	v_mov_b32_e32 v56, v2
	v_mov_b32_e32 v57, v2
	v_mov_b32_e32 v10, v2
	v_mov_b32_e32 v11, v2
	v_mov_b32_e32 v12, v2
	v_mov_b32_e32 v13, v2
	v_mov_b32_e32 v14, v2
	v_mov_b32_e32 v15, v2
	v_mov_b32_e32 v16, v2
	v_mov_b32_e32 v17, v2
	v_mov_b32_e32 v26, v2
	v_mov_b32_e32 v27, v2
	v_mov_b32_e32 v28, v2
	v_mov_b32_e32 v29, v2
	v_mov_b32_e32 v30, v2
	v_mov_b32_e32 v31, v2
	v_mov_b32_e32 v32, v2
	v_mov_b32_e32 v33, v2
	v_mov_b32_e32 v42, v2
	v_mov_b32_e32 v43, v2
	v_mov_b32_e32 v44, v2
	v_mov_b32_e32 v45, v2
	v_mov_b32_e32 v46, v2
	v_mov_b32_e32 v47, v2
	v_mov_b32_e32 v48, v2
	v_mov_b32_e32 v49, v2
	v_mov_b32_e32 v58, v2
	v_mov_b32_e32 v59, v2
	v_mov_b32_e32 v60, v2
	v_mov_b32_e32 v61, v2
	v_mov_b32_e32 v62, v2
	v_mov_b32_e32 v63, v2
	v_mov_b32_e32 v64, v2
	v_mov_b32_e32 v65, v2
	v_mov_b32_e32 v66, v2
	v_mov_b32_e32 v67, v2
	v_mov_b32_e32 v68, v2
	v_mov_b32_e32 v69, v2
	v_mov_b32_e32 v70, v2
	v_mov_b32_e32 v71, v2
	v_mov_b32_e32 v72, v2
	v_mov_b32_e32 v73, v2
	v_mov_b32_e32 v82, v2
	v_mov_b32_e32 v83, v2
	v_mov_b32_e32 v84, v2
	v_mov_b32_e32 v85, v2
	v_mov_b32_e32 v86, v2
	v_mov_b32_e32 v87, v2
	v_mov_b32_e32 v88, v2
	v_mov_b32_e32 v89, v2
	v_mov_b32_e32 v98, v2
	v_mov_b32_e32 v99, v2
	v_mov_b32_e32 v100, v2
	v_mov_b32_e32 v101, v2
	v_mov_b32_e32 v102, v2
	v_mov_b32_e32 v103, v2
	v_mov_b32_e32 v104, v2
	v_mov_b32_e32 v105, v2
	v_mov_b32_e32 v114, v2
	v_mov_b32_e32 v115, v2
	v_mov_b32_e32 v116, v2
	v_mov_b32_e32 v117, v2
	v_mov_b32_e32 v118, v2
	v_mov_b32_e32 v119, v2
	v_mov_b32_e32 v120, v2
	v_mov_b32_e32 v121, v2
	v_mov_b32_e32 v74, v2
	v_mov_b32_e32 v75, v2
	v_mov_b32_e32 v76, v2
	v_mov_b32_e32 v77, v2
	v_mov_b32_e32 v78, v2
	v_mov_b32_e32 v79, v2
	v_mov_b32_e32 v80, v2
	v_mov_b32_e32 v81, v2
	v_mov_b32_e32 v90, v2
	v_mov_b32_e32 v91, v2
	v_mov_b32_e32 v92, v2
	v_mov_b32_e32 v93, v2
	v_mov_b32_e32 v94, v2
	v_mov_b32_e32 v95, v2
	v_mov_b32_e32 v96, v2
	v_mov_b32_e32 v97, v2
	v_mov_b32_e32 v106, v2
	v_mov_b32_e32 v107, v2
	v_mov_b32_e32 v108, v2
	v_mov_b32_e32 v109, v2
	v_mov_b32_e32 v110, v2
	v_mov_b32_e32 v111, v2
	v_mov_b32_e32 v112, v2
	v_mov_b32_e32 v113, v2
	v_mov_b32_e32 v126, v2
	v_mov_b32_e32 v127, v2
	v_mov_b32_e32 v128, v2
	v_mov_b32_e32 v129, v2
	v_mov_b32_e32 v138, v2
	v_mov_b32_e32 v139, v2
	v_mov_b32_e32 v140, v2
	v_mov_b32_e32 v141, v2
	s_branch .LBB0_215

.LBB0_353:
	ds_read_b128 v[136:139], v153
	ds_read_b128 v[140:143], v153 offset:1024
	ds_read_b128 v[158:161], v153 offset:2048
	ds_read_b128 v[162:165], v153 offset:3072
	ds_read_b128 v[166:169], v154
	ds_read_b128 v[170:173], v154 offset:1024
	ds_read_b128 v[174:177], v154 offset:2048
	ds_read_b128 v[178:181], v154 offset:3072
	s_add_i32 s66, s63, 0xfffe0080
	s_cmp_eq_u32 s65, 4
	s_cselect_b32 s68, s1, s66
	s_cselect_b32 s67, s62, s64
	s_or_b32 s66, s68, 0x80
	s_mov_b32 m0, s48
	s_nop 0
	buffer_load_dwordx4 v147, s[12:15], s63 offen lds
	s_nop 0
	s_mov_b32 m0, s49
	s_nop 0
	buffer_load_dwordx4 v148, s[12:15], s63 offen lds
	ds_read_b128 v[182:185], v155
	ds_read_b128 v[186:189], v155 offset:1024
	ds_read_b128 v[190:193], v155 offset:2048
	ds_read_b128 v[194:197], v155 offset:3072
	ds_read_b128 v[198:201], v155 offset:4096
	ds_read_b128 v[202:205], v155 offset:5120
	ds_read_b128 v[206:209], v155 offset:6144
	ds_read_b128 v[210:213], v155 offset:7168
	s_waitcnt vmcnt(8)
	s_waitcnt lgkmcnt(0)
	s_setprio 1
	s_barrier
	v_mfma_i32_16x16x64_i8 v[126:129], v[136:139], v[182:185], v[126:129]
	v_mfma_i32_16x16x64_i8 v[122:125], v[158:161], v[182:185], v[122:125]
	v_mfma_i32_16x16x64_i8 v[118:121], v[136:139], v[190:193], v[118:121]
	v_mfma_i32_16x16x64_i8 v[114:117], v[158:161], v[190:193], v[114:117]
	v_mfma_i32_16x16x64_i8 v[110:113], v[136:139], v[198:201], v[110:113]
	v_mfma_i32_16x16x64_i8 v[106:109], v[158:161], v[198:201], v[106:109]
	v_mfma_i32_16x16x64_i8 v[102:105], v[136:139], v[206:209], v[102:105]
	v_mfma_i32_16x16x64_i8 v[98:101], v[158:161], v[206:209], v[98:101]
	v_mfma_i32_16x16x64_i8 v[126:129], v[140:143], v[186:189], v[126:129]
	v_mfma_i32_16x16x64_i8 v[122:125], v[162:165], v[186:189], v[122:125]
	v_mfma_i32_16x16x64_i8 v[118:121], v[140:143], v[194:197], v[118:121]
	v_mfma_i32_16x16x64_i8 v[114:117], v[162:165], v[194:197], v[114:117]
	v_mfma_i32_16x16x64_i8 v[110:113], v[140:143], v[202:205], v[110:113]
	v_mfma_i32_16x16x64_i8 v[106:109], v[162:165], v[202:205], v[106:109]
	v_mfma_i32_16x16x64_i8 v[102:105], v[140:143], v[210:213], v[102:105]
	v_mfma_i32_16x16x64_i8 v[98:101], v[162:165], v[210:213], v[98:101]
	s_setprio 0
	s_setprio 1
	v_mfma_i32_16x16x64_i8 v[94:97], v[166:169], v[182:185], v[94:97]
	v_mfma_i32_16x16x64_i8 v[90:93], v[174:177], v[182:185], v[90:93]
	v_mfma_i32_16x16x64_i8 v[86:89], v[166:169], v[190:193], v[86:89]
	v_mfma_i32_16x16x64_i8 v[82:85], v[174:177], v[190:193], v[82:85]
	v_mfma_i32_16x16x64_i8 v[78:81], v[166:169], v[198:201], v[78:81]
	v_mfma_i32_16x16x64_i8 v[74:77], v[174:177], v[198:201], v[74:77]
	v_mfma_i32_16x16x64_i8 v[70:73], v[166:169], v[206:209], v[70:73]
	v_mfma_i32_16x16x64_i8 v[66:69], v[174:177], v[206:209], v[66:69]
	v_mfma_i32_16x16x64_i8 v[94:97], v[170:173], v[186:189], v[94:97]
	v_mfma_i32_16x16x64_i8 v[90:93], v[178:181], v[186:189], v[90:93]
	v_mfma_i32_16x16x64_i8 v[86:89], v[170:173], v[194:197], v[86:89]
	v_mfma_i32_16x16x64_i8 v[82:85], v[178:181], v[194:197], v[82:85]
	v_mfma_i32_16x16x64_i8 v[78:81], v[170:173], v[202:205], v[78:81]
	v_mfma_i32_16x16x64_i8 v[74:77], v[178:181], v[202:205], v[74:77]
	v_mfma_i32_16x16x64_i8 v[70:73], v[170:173], v[210:213], v[70:73]
	v_mfma_i32_16x16x64_i8 v[66:69], v[178:181], v[210:213], v[66:69]
	s_barrier
	s_setprio 0
	ds_read_b128 v[182:185], v155 offset:16384
	ds_read_b128 v[186:189], v155 offset:17408
	s_mov_b32 m0, s34
	s_nop 0
	buffer_load_dwordx4 v145, s[8:11], s67 offen lds
	ds_read_b128 v[190:193], v155 offset:18432
	ds_read_b128 v[194:197], v155 offset:19456
	s_add_i32 s69, s67, 0x20000
	s_mov_b32 m0, s35
	s_nop 0
	buffer_load_dwordx4 v146, s[8:11], s67 offen lds
	ds_read_b128 v[198:201], v155 offset:20480
	ds_read_b128 v[202:205], v155 offset:21504
	s_nop 0
	s_mov_b32 m0, s36
	s_nop 0
	buffer_load_dwordx4 v145, s[8:11], s69 offen lds
	ds_read_b128 v[206:209], v155 offset:22528
	ds_read_b128 v[210:213], v155 offset:23552
	s_nop 0
	s_mov_b32 m0, s37
	s_nop 0
	buffer_load_dwordx4 v146, s[8:11], s69 offen lds
	s_nop 0
	s_mov_b32 m0, s33
	s_nop 0
	buffer_load_dwordx4 v147, s[12:15], s68 offen lds
	s_nop 0
	s_mov_b32 m0, s2
	s_nop 0
	buffer_load_dwordx4 v148, s[12:15], s68 offen lds
	s_waitcnt vmcnt(8)
	s_waitcnt lgkmcnt(0)
	s_setprio 1
	s_barrier
	v_mfma_i32_16x16x64_i8 v[62:65], v[136:139], v[182:185], v[62:65]
	v_mfma_i32_16x16x64_i8 v[58:61], v[158:161], v[182:185], v[58:61]
	v_mfma_i32_16x16x64_i8 v[54:57], v[136:139], v[190:193], v[54:57]
	v_mfma_i32_16x16x64_i8 v[50:53], v[158:161], v[190:193], v[50:53]
	v_mfma_i32_16x16x64_i8 v[46:49], v[136:139], v[198:201], v[46:49]
	v_mfma_i32_16x16x64_i8 v[42:45], v[158:161], v[198:201], v[42:45]
	v_mfma_i32_16x16x64_i8 v[38:41], v[136:139], v[206:209], v[38:41]
	v_mfma_i32_16x16x64_i8 v[34:37], v[158:161], v[206:209], v[34:37]
	v_mfma_i32_16x16x64_i8 v[62:65], v[140:143], v[186:189], v[62:65]
	v_mfma_i32_16x16x64_i8 v[58:61], v[162:165], v[186:189], v[58:61]
	v_mfma_i32_16x16x64_i8 v[54:57], v[140:143], v[194:197], v[54:57]
	v_mfma_i32_16x16x64_i8 v[50:53], v[162:165], v[194:197], v[50:53]
	v_mfma_i32_16x16x64_i8 v[46:49], v[140:143], v[202:205], v[46:49]
	v_mfma_i32_16x16x64_i8 v[42:45], v[162:165], v[202:205], v[42:45]
	v_mfma_i32_16x16x64_i8 v[38:41], v[140:143], v[210:213], v[38:41]
	v_mfma_i32_16x16x64_i8 v[34:37], v[162:165], v[210:213], v[34:37]
	s_setprio 0
	s_setprio 1
	v_mfma_i32_16x16x64_i8 v[30:33], v[166:169], v[182:185], v[30:33]
	v_mfma_i32_16x16x64_i8 v[26:29], v[174:177], v[182:185], v[26:29]
	v_mfma_i32_16x16x64_i8 v[22:25], v[166:169], v[190:193], v[22:25]
	v_mfma_i32_16x16x64_i8 v[18:21], v[174:177], v[190:193], v[18:21]
	v_mfma_i32_16x16x64_i8 v[14:17], v[166:169], v[198:201], v[14:17]
	v_mfma_i32_16x16x64_i8 v[10:13], v[174:177], v[198:201], v[10:13]
	v_mfma_i32_16x16x64_i8 v[6:9], v[166:169], v[206:209], v[6:9]
	v_mfma_i32_16x16x64_i8 v[2:5], v[174:177], v[206:209], v[2:5]
	v_mfma_i32_16x16x64_i8 v[30:33], v[170:173], v[186:189], v[30:33]
	v_mfma_i32_16x16x64_i8 v[26:29], v[178:181], v[186:189], v[26:29]
	v_mfma_i32_16x16x64_i8 v[22:25], v[170:173], v[194:197], v[22:25]
	v_mfma_i32_16x16x64_i8 v[18:21], v[178:181], v[194:197], v[18:21]
	v_mfma_i32_16x16x64_i8 v[14:17], v[170:173], v[202:205], v[14:17]
	v_mfma_i32_16x16x64_i8 v[10:13], v[178:181], v[202:205], v[10:13]
	v_mfma_i32_16x16x64_i8 v[6:9], v[170:173], v[210:213], v[6:9]
	v_mfma_i32_16x16x64_i8 v[2:5], v[178:181], v[210:213], v[2:5]
	s_barrier
	s_setprio 0
	ds_read_b128 v[136:139], v156
	ds_read_b128 v[140:143], v156 offset:1024
	ds_read_b128 v[158:161], v156 offset:2048
	ds_read_b128 v[162:165], v156 offset:3072
	ds_read_b128 v[166:169], v157
	ds_read_b128 v[170:173], v157 offset:1024
	ds_read_b128 v[174:177], v157 offset:2048
	ds_read_b128 v[178:181], v157 offset:3072
	s_add_i32 s68, s68, 0x20000
	s_mov_b32 m0, s3
	s_nop 0
	buffer_load_dwordx4 v147, s[12:15], s68 offen lds
	s_nop 0
	s_mov_b32 m0, s38
	s_nop 0
	buffer_load_dwordx4 v148, s[12:15], s68 offen lds
	ds_read_b128 v[182:185], v155 offset:32768
	ds_read_b128 v[186:189], v155 offset:33792
	ds_read_b128 v[190:193], v155 offset:34816
	ds_read_b128 v[194:197], v155 offset:35840
	ds_read_b128 v[198:201], v155 offset:36864
	ds_read_b128 v[202:205], v155 offset:37888
	ds_read_b128 v[206:209], v155 offset:38912
	ds_read_b128 v[210:213], v155 offset:39936
	s_waitcnt vmcnt(8)
	s_waitcnt lgkmcnt(0)
	s_setprio 1
	s_barrier
	v_mfma_i32_16x16x64_i8 v[126:129], v[136:139], v[182:185], v[126:129]
	v_mfma_i32_16x16x64_i8 v[122:125], v[158:161], v[182:185], v[122:125]
	v_mfma_i32_16x16x64_i8 v[118:121], v[136:139], v[190:193], v[118:121]
	v_mfma_i32_16x16x64_i8 v[114:117], v[158:161], v[190:193], v[114:117]
	v_mfma_i32_16x16x64_i8 v[110:113], v[136:139], v[198:201], v[110:113]
	v_mfma_i32_16x16x64_i8 v[106:109], v[158:161], v[198:201], v[106:109]
	v_mfma_i32_16x16x64_i8 v[102:105], v[136:139], v[206:209], v[102:105]
	v_mfma_i32_16x16x64_i8 v[98:101], v[158:161], v[206:209], v[98:101]
	v_mfma_i32_16x16x64_i8 v[126:129], v[140:143], v[186:189], v[126:129]
	v_mfma_i32_16x16x64_i8 v[122:125], v[162:165], v[186:189], v[122:125]
	v_mfma_i32_16x16x64_i8 v[118:121], v[140:143], v[194:197], v[118:121]
	v_mfma_i32_16x16x64_i8 v[114:117], v[162:165], v[194:197], v[114:117]
	v_mfma_i32_16x16x64_i8 v[110:113], v[140:143], v[202:205], v[110:113]
	v_mfma_i32_16x16x64_i8 v[106:109], v[162:165], v[202:205], v[106:109]
	v_mfma_i32_16x16x64_i8 v[102:105], v[140:143], v[210:213], v[102:105]
	v_mfma_i32_16x16x64_i8 v[98:101], v[162:165], v[210:213], v[98:101]
	s_setprio 0
	s_setprio 1
	v_mfma_i32_16x16x64_i8 v[94:97], v[166:169], v[182:185], v[94:97]
	v_mfma_i32_16x16x64_i8 v[90:93], v[174:177], v[182:185], v[90:93]
	v_mfma_i32_16x16x64_i8 v[86:89], v[166:169], v[190:193], v[86:89]
	v_mfma_i32_16x16x64_i8 v[82:85], v[174:177], v[190:193], v[82:85]
	v_mfma_i32_16x16x64_i8 v[78:81], v[166:169], v[198:201], v[78:81]
	v_mfma_i32_16x16x64_i8 v[74:77], v[174:177], v[198:201], v[74:77]
	v_mfma_i32_16x16x64_i8 v[70:73], v[166:169], v[206:209], v[70:73]
	v_mfma_i32_16x16x64_i8 v[66:69], v[174:177], v[206:209], v[66:69]
	v_mfma_i32_16x16x64_i8 v[94:97], v[170:173], v[186:189], v[94:97]
	v_mfma_i32_16x16x64_i8 v[90:93], v[178:181], v[186:189], v[90:93]
	v_mfma_i32_16x16x64_i8 v[86:89], v[170:173], v[194:197], v[86:89]
	v_mfma_i32_16x16x64_i8 v[82:85], v[178:181], v[194:197], v[82:85]
	v_mfma_i32_16x16x64_i8 v[78:81], v[170:173], v[202:205], v[78:81]
	v_mfma_i32_16x16x64_i8 v[74:77], v[178:181], v[202:205], v[74:77]
	v_mfma_i32_16x16x64_i8 v[70:73], v[170:173], v[210:213], v[70:73]
	v_mfma_i32_16x16x64_i8 v[66:69], v[178:181], v[210:213], v[66:69]
	s_barrier
	s_setprio 0
	ds_read_b128 v[182:185], v155 offset:49152
	ds_read_b128 v[186:189], v155 offset:50176
	s_or_b32 s68, s67, 0x80
	s_mov_b32 m0, s41
	s_nop 0
	buffer_load_dwordx4 v145, s[8:11], s68 offen lds
	ds_read_b128 v[190:193], v155 offset:51200
	ds_read_b128 v[194:197], v155 offset:52224
	s_add_i32 s67, s67, 0x20080
	s_mov_b32 m0, s42
	s_nop 0
	buffer_load_dwordx4 v146, s[8:11], s68 offen lds
	ds_read_b128 v[198:201], v155 offset:53248
	ds_read_b128 v[202:205], v155 offset:54272
	s_nop 0
	s_mov_b32 m0, s45
	s_nop 0
	buffer_load_dwordx4 v145, s[8:11], s67 offen lds
	ds_read_b128 v[206:209], v155 offset:55296
	ds_read_b128 v[210:213], v155 offset:56320
	s_nop 0
	s_mov_b32 m0, s46
	s_nop 0
	buffer_load_dwordx4 v146, s[8:11], s67 offen lds
	s_nop 0
	s_mov_b32 m0, s43
	s_nop 0
	buffer_load_dwordx4 v147, s[12:15], s66 offen lds
	s_nop 0
	s_mov_b32 m0, s44
	s_nop 0
	buffer_load_dwordx4 v148, s[12:15], s66 offen lds
	s_waitcnt vmcnt(8)
	s_waitcnt lgkmcnt(0)
	s_setprio 1
	s_barrier
	v_mfma_i32_16x16x64_i8 v[62:65], v[136:139], v[182:185], v[62:65]
	v_mfma_i32_16x16x64_i8 v[58:61], v[158:161], v[182:185], v[58:61]
	v_mfma_i32_16x16x64_i8 v[54:57], v[136:139], v[190:193], v[54:57]
	v_mfma_i32_16x16x64_i8 v[50:53], v[158:161], v[190:193], v[50:53]
	v_mfma_i32_16x16x64_i8 v[46:49], v[136:139], v[198:201], v[46:49]
	v_mfma_i32_16x16x64_i8 v[42:45], v[158:161], v[198:201], v[42:45]
	v_mfma_i32_16x16x64_i8 v[38:41], v[136:139], v[206:209], v[38:41]
	v_mfma_i32_16x16x64_i8 v[34:37], v[158:161], v[206:209], v[34:37]
	v_mfma_i32_16x16x64_i8 v[62:65], v[140:143], v[186:189], v[62:65]
	v_mfma_i32_16x16x64_i8 v[58:61], v[162:165], v[186:189], v[58:61]
	v_mfma_i32_16x16x64_i8 v[54:57], v[140:143], v[194:197], v[54:57]
	v_mfma_i32_16x16x64_i8 v[50:53], v[162:165], v[194:197], v[50:53]
	v_mfma_i32_16x16x64_i8 v[46:49], v[140:143], v[202:205], v[46:49]
	v_mfma_i32_16x16x64_i8 v[42:45], v[162:165], v[202:205], v[42:45]
	v_mfma_i32_16x16x64_i8 v[38:41], v[140:143], v[210:213], v[38:41]
	v_mfma_i32_16x16x64_i8 v[34:37], v[162:165], v[210:213], v[34:37]
	s_setprio 0
	s_setprio 1
	v_mfma_i32_16x16x64_i8 v[30:33], v[166:169], v[182:185], v[30:33]
	v_mfma_i32_16x16x64_i8 v[26:29], v[174:177], v[182:185], v[26:29]
	v_mfma_i32_16x16x64_i8 v[22:25], v[166:169], v[190:193], v[22:25]
	v_mfma_i32_16x16x64_i8 v[18:21], v[174:177], v[190:193], v[18:21]
	v_mfma_i32_16x16x64_i8 v[14:17], v[166:169], v[198:201], v[14:17]
	v_mfma_i32_16x16x64_i8 v[10:13], v[174:177], v[198:201], v[10:13]
	v_mfma_i32_16x16x64_i8 v[6:9], v[166:169], v[206:209], v[6:9]
	v_mfma_i32_16x16x64_i8 v[2:5], v[174:177], v[206:209], v[2:5]
	v_mfma_i32_16x16x64_i8 v[30:33], v[170:173], v[186:189], v[30:33]
	v_mfma_i32_16x16x64_i8 v[26:29], v[178:181], v[186:189], v[26:29]
	v_mfma_i32_16x16x64_i8 v[22:25], v[170:173], v[194:197], v[22:25]
	v_mfma_i32_16x16x64_i8 v[18:21], v[178:181], v[194:197], v[18:21]
	v_mfma_i32_16x16x64_i8 v[14:17], v[170:173], v[202:205], v[14:17]
	v_mfma_i32_16x16x64_i8 v[10:13], v[178:181], v[202:205], v[10:13]
	v_mfma_i32_16x16x64_i8 v[6:9], v[170:173], v[210:213], v[6:9]
	v_mfma_i32_16x16x64_i8 v[2:5], v[178:181], v[210:213], v[2:5]
	s_barrier
	s_setprio 0
	s_add_i32 s65, s65, 2
	s_addk_i32 s63, 0x100
	s_addk_i32 s64, 0x100
	s_cmp_gt_u32 s65, 5
	s_cbranch_scc0 .LBB0_353
	s_and_b64 vcc, exec, s[24:25]
	s_cbranch_vccz .LBB0_356
	s_barrier

.LBB0_467:
	v_add_u32_e32 v147, 0x10000, v132
	ds_read_b128 v[138:141], v147
	ds_read_b128 v[142:145], v147 offset:1024
	ds_read_b128 v[148:151], v147 offset:2048
	ds_read_b128 v[152:155], v147 offset:3072
	v_add_u32_e32 v147, 0x14000, v132
	ds_read_b128 v[156:159], v147
	ds_read_b128 v[160:163], v147 offset:1024
	ds_read_b128 v[164:167], v147 offset:2048
	ds_read_b128 v[168:171], v147 offset:3072
	s_add_i32 s59, s3, s1
	s_add_i32 s58, s33, s1
	s_add_i32 s55, s59, 0x1600
	s_addk_i32 s58, 0x1600
	s_cmp_eq_u32 s1, 0
	s_cselect_b32 s60, s53, s55
	s_cselect_b32 s58, s54, s58
	s_add_i32 s55, s60, 0x80
	s_add_i32 s59, s59, 0xb1580
	s_mov_b32 m0, s46
	s_nop 0
	buffer_load_dwordx4 v130, s[12:15], s59 offen lds
	s_nop 0
	s_mov_b32 m0, s47
	s_nop 0
	buffer_load_dwordx4 v131, s[12:15], s59 offen lds
	ds_read_b128 v[172:175], v133
	ds_read_b128 v[176:179], v133 offset:1024
	ds_read_b128 v[180:183], v133 offset:2048
	ds_read_b128 v[184:187], v133 offset:3072
	ds_read_b128 v[188:191], v133 offset:4096
	ds_read_b128 v[192:195], v133 offset:5120
	ds_read_b128 v[196:199], v133 offset:6144
	ds_read_b128 v[200:203], v133 offset:7168
	s_waitcnt vmcnt(8)
	s_waitcnt lgkmcnt(0)
	s_setprio 1
	s_barrier
	v_mfma_f32_16x16x32_bf16 v[134:137], v[138:141], v[172:175], v[134:137]
	v_mfma_f32_16x16x32_bf16 v[122:125], v[148:151], v[172:175], v[122:125]
	v_mfma_f32_16x16x32_bf16 v[110:113], v[138:141], v[180:183], v[110:113]
	v_mfma_f32_16x16x32_bf16 v[106:109], v[148:151], v[180:183], v[106:109]
	v_mfma_f32_16x16x32_bf16 v[94:97], v[138:141], v[188:191], v[94:97]
	v_mfma_f32_16x16x32_bf16 v[90:93], v[148:151], v[188:191], v[90:93]
	v_mfma_f32_16x16x32_bf16 v[78:81], v[138:141], v[196:199], v[78:81]
	v_mfma_f32_16x16x32_bf16 v[74:77], v[148:151], v[196:199], v[74:77]
	v_mfma_f32_16x16x32_bf16 v[134:137], v[142:145], v[176:179], v[134:137]
	v_mfma_f32_16x16x32_bf16 v[122:125], v[152:155], v[176:179], v[122:125]
	v_mfma_f32_16x16x32_bf16 v[110:113], v[142:145], v[184:187], v[110:113]
	v_mfma_f32_16x16x32_bf16 v[106:109], v[152:155], v[184:187], v[106:109]
	v_mfma_f32_16x16x32_bf16 v[94:97], v[142:145], v[192:195], v[94:97]
	v_mfma_f32_16x16x32_bf16 v[90:93], v[152:155], v[192:195], v[90:93]
	v_mfma_f32_16x16x32_bf16 v[78:81], v[142:145], v[200:203], v[78:81]
	v_mfma_f32_16x16x32_bf16 v[74:77], v[152:155], v[200:203], v[74:77]
	s_setprio 0
	s_setprio 1
	v_mfma_f32_16x16x32_bf16 v[118:121], v[156:159], v[172:175], v[118:121]
	v_mfma_f32_16x16x32_bf16 v[114:117], v[164:167], v[172:175], v[114:117]
	v_mfma_f32_16x16x32_bf16 v[102:105], v[156:159], v[180:183], v[102:105]
	v_mfma_f32_16x16x32_bf16 v[98:101], v[164:167], v[180:183], v[98:101]
	v_mfma_f32_16x16x32_bf16 v[86:89], v[156:159], v[188:191], v[86:89]
	v_mfma_f32_16x16x32_bf16 v[82:85], v[164:167], v[188:191], v[82:85]
	v_mfma_f32_16x16x32_bf16 v[70:73], v[156:159], v[196:199], v[70:73]
	v_mfma_f32_16x16x32_bf16 v[66:69], v[164:167], v[196:199], v[66:69]
	v_mfma_f32_16x16x32_bf16 v[118:121], v[160:163], v[176:179], v[118:121]
	v_mfma_f32_16x16x32_bf16 v[114:117], v[168:171], v[176:179], v[114:117]
	v_mfma_f32_16x16x32_bf16 v[102:105], v[160:163], v[184:187], v[102:105]
	v_mfma_f32_16x16x32_bf16 v[98:101], v[168:171], v[184:187], v[98:101]
	v_mfma_f32_16x16x32_bf16 v[86:89], v[160:163], v[192:195], v[86:89]
	v_mfma_f32_16x16x32_bf16 v[82:85], v[168:171], v[192:195], v[82:85]
	v_mfma_f32_16x16x32_bf16 v[70:73], v[160:163], v[200:203], v[70:73]
	v_mfma_f32_16x16x32_bf16 v[66:69], v[168:171], v[200:203], v[66:69]
	s_barrier
	s_setprio 0
	ds_read_b128 v[172:175], v133 offset:16384
	ds_read_b128 v[176:179], v133 offset:17408
	s_mov_b32 m0, s29
	s_nop 0
	buffer_load_dwordx4 v130, s[8:11], s58 offen lds
	ds_read_b128 v[180:183], v133 offset:18432
	ds_read_b128 v[184:187], v133 offset:19456
	s_add_i32 s59, s58, 0xb0000
	s_mov_b32 m0, s34
	s_nop 0
	buffer_load_dwordx4 v131, s[8:11], s58 offen lds
	ds_read_b128 v[188:191], v133 offset:20480
	ds_read_b128 v[192:195], v133 offset:21504
	s_nop 0
	s_mov_b32 m0, s35
	s_nop 0
	buffer_load_dwordx4 v130, s[8:11], s59 offen lds
	ds_read_b128 v[196:199], v133 offset:22528
	ds_read_b128 v[200:203], v133 offset:23552
	s_nop 0
	s_mov_b32 m0, s36
	s_nop 0
	buffer_load_dwordx4 v131, s[8:11], s59 offen lds
	s_nop 0
	s_mov_b32 m0, s28
	s_nop 0
	buffer_load_dwordx4 v130, s[12:15], s60 offen lds
	s_nop 0
	s_mov_b32 m0, s37
	s_nop 0
	buffer_load_dwordx4 v131, s[12:15], s60 offen lds
	s_waitcnt vmcnt(8)
	s_waitcnt lgkmcnt(0)
	s_setprio 1
	s_barrier
	v_mfma_f32_16x16x32_bf16 v[62:65], v[138:141], v[172:175], v[62:65]
	v_mfma_f32_16x16x32_bf16 v[58:61], v[148:151], v[172:175], v[58:61]
	v_mfma_f32_16x16x32_bf16 v[46:49], v[138:141], v[180:183], v[46:49]
	v_mfma_f32_16x16x32_bf16 v[42:45], v[148:151], v[180:183], v[42:45]
	v_mfma_f32_16x16x32_bf16 v[30:33], v[138:141], v[188:191], v[30:33]
	v_mfma_f32_16x16x32_bf16 v[26:29], v[148:151], v[188:191], v[26:29]
	v_mfma_f32_16x16x32_bf16 v[14:17], v[138:141], v[196:199], v[14:17]
	v_mfma_f32_16x16x32_bf16 v[10:13], v[148:151], v[196:199], v[10:13]
	v_mfma_f32_16x16x32_bf16 v[62:65], v[142:145], v[176:179], v[62:65]
	v_mfma_f32_16x16x32_bf16 v[58:61], v[152:155], v[176:179], v[58:61]
	v_mfma_f32_16x16x32_bf16 v[46:49], v[142:145], v[184:187], v[46:49]
	v_mfma_f32_16x16x32_bf16 v[42:45], v[152:155], v[184:187], v[42:45]
	v_mfma_f32_16x16x32_bf16 v[30:33], v[142:145], v[192:195], v[30:33]
	v_mfma_f32_16x16x32_bf16 v[26:29], v[152:155], v[192:195], v[26:29]
	v_mfma_f32_16x16x32_bf16 v[14:17], v[142:145], v[200:203], v[14:17]
	v_mfma_f32_16x16x32_bf16 v[10:13], v[152:155], v[200:203], v[10:13]
	s_setprio 0
	s_setprio 1
	v_mfma_f32_16x16x32_bf16 v[54:57], v[156:159], v[172:175], v[54:57]
	v_mfma_f32_16x16x32_bf16 v[50:53], v[164:167], v[172:175], v[50:53]
	v_mfma_f32_16x16x32_bf16 v[38:41], v[156:159], v[180:183], v[38:41]
	v_mfma_f32_16x16x32_bf16 v[34:37], v[164:167], v[180:183], v[34:37]
	v_mfma_f32_16x16x32_bf16 v[22:25], v[156:159], v[188:191], v[22:25]
	v_mfma_f32_16x16x32_bf16 v[18:21], v[164:167], v[188:191], v[18:21]
	v_mfma_f32_16x16x32_bf16 v[6:9], v[156:159], v[196:199], v[6:9]
	v_mfma_f32_16x16x32_bf16 v[2:5], v[164:167], v[196:199], v[2:5]
	v_mfma_f32_16x16x32_bf16 v[54:57], v[160:163], v[176:179], v[54:57]
	v_mfma_f32_16x16x32_bf16 v[50:53], v[168:171], v[176:179], v[50:53]
	v_mfma_f32_16x16x32_bf16 v[38:41], v[160:163], v[184:187], v[38:41]
	v_mfma_f32_16x16x32_bf16 v[34:37], v[168:171], v[184:187], v[34:37]
	v_mfma_f32_16x16x32_bf16 v[22:25], v[160:163], v[192:195], v[22:25]
	v_mfma_f32_16x16x32_bf16 v[18:21], v[168:171], v[192:195], v[18:21]
	v_mfma_f32_16x16x32_bf16 v[6:9], v[160:163], v[200:203], v[6:9]
	v_mfma_f32_16x16x32_bf16 v[2:5], v[168:171], v[200:203], v[2:5]
	s_barrier
	s_setprio 0
	v_add_u32_e32 v147, 0x18000, v132
	ds_read_b128 v[138:141], v147
	ds_read_b128 v[142:145], v147 offset:1024
	ds_read_b128 v[148:151], v147 offset:2048
	ds_read_b128 v[152:155], v147 offset:3072
	v_add_u32_e32 v147, 0x1c000, v132
	ds_read_b128 v[156:159], v147
	ds_read_b128 v[160:163], v147 offset:1024
	ds_read_b128 v[164:167], v147 offset:2048
	ds_read_b128 v[168:171], v147 offset:3072
	s_add_i32 s59, s60, 0xb0000
	s_mov_b32 m0, s38
	s_nop 0
	buffer_load_dwordx4 v130, s[12:15], s59 offen lds
	s_nop 0
	s_mov_b32 m0, s39
	s_nop 0
	buffer_load_dwordx4 v131, s[12:15], s59 offen lds
	ds_read_b128 v[172:175], v133 offset:32768
	ds_read_b128 v[176:179], v133 offset:33792
	ds_read_b128 v[180:183], v133 offset:34816
	ds_read_b128 v[184:187], v133 offset:35840
	ds_read_b128 v[188:191], v133 offset:36864
	ds_read_b128 v[192:195], v133 offset:37888
	ds_read_b128 v[196:199], v133 offset:38912
	ds_read_b128 v[200:203], v133 offset:39936
	s_waitcnt vmcnt(8)
	s_waitcnt lgkmcnt(0)
	s_setprio 1
	s_barrier
	v_mfma_f32_16x16x32_bf16 v[134:137], v[138:141], v[172:175], v[134:137]
	v_mfma_f32_16x16x32_bf16 v[122:125], v[148:151], v[172:175], v[122:125]
	v_mfma_f32_16x16x32_bf16 v[110:113], v[138:141], v[180:183], v[110:113]
	v_mfma_f32_16x16x32_bf16 v[106:109], v[148:151], v[180:183], v[106:109]
	v_mfma_f32_16x16x32_bf16 v[94:97], v[138:141], v[188:191], v[94:97]
	v_mfma_f32_16x16x32_bf16 v[90:93], v[148:151], v[188:191], v[90:93]
	v_mfma_f32_16x16x32_bf16 v[78:81], v[138:141], v[196:199], v[78:81]
	v_mfma_f32_16x16x32_bf16 v[74:77], v[148:151], v[196:199], v[74:77]
	v_mfma_f32_16x16x32_bf16 v[134:137], v[142:145], v[176:179], v[134:137]
	v_mfma_f32_16x16x32_bf16 v[122:125], v[152:155], v[176:179], v[122:125]
	v_mfma_f32_16x16x32_bf16 v[110:113], v[142:145], v[184:187], v[110:113]
	v_mfma_f32_16x16x32_bf16 v[106:109], v[152:155], v[184:187], v[106:109]
	v_mfma_f32_16x16x32_bf16 v[94:97], v[142:145], v[192:195], v[94:97]
	v_mfma_f32_16x16x32_bf16 v[90:93], v[152:155], v[192:195], v[90:93]
	v_mfma_f32_16x16x32_bf16 v[78:81], v[142:145], v[200:203], v[78:81]
	v_mfma_f32_16x16x32_bf16 v[74:77], v[152:155], v[200:203], v[74:77]
	s_setprio 0
	s_setprio 1
	v_mfma_f32_16x16x32_bf16 v[118:121], v[156:159], v[172:175], v[118:121]
	v_mfma_f32_16x16x32_bf16 v[114:117], v[164:167], v[172:175], v[114:117]
	v_mfma_f32_16x16x32_bf16 v[102:105], v[156:159], v[180:183], v[102:105]
	v_mfma_f32_16x16x32_bf16 v[98:101], v[164:167], v[180:183], v[98:101]
	v_mfma_f32_16x16x32_bf16 v[86:89], v[156:159], v[188:191], v[86:89]
	v_mfma_f32_16x16x32_bf16 v[82:85], v[164:167], v[188:191], v[82:85]
	v_mfma_f32_16x16x32_bf16 v[70:73], v[156:159], v[196:199], v[70:73]
	v_mfma_f32_16x16x32_bf16 v[66:69], v[164:167], v[196:199], v[66:69]
	v_mfma_f32_16x16x32_bf16 v[118:121], v[160:163], v[176:179], v[118:121]
	v_mfma_f32_16x16x32_bf16 v[114:117], v[168:171], v[176:179], v[114:117]
	v_mfma_f32_16x16x32_bf16 v[102:105], v[160:163], v[184:187], v[102:105]
	v_mfma_f32_16x16x32_bf16 v[98:101], v[168:171], v[184:187], v[98:101]
	v_mfma_f32_16x16x32_bf16 v[86:89], v[160:163], v[192:195], v[86:89]
	v_mfma_f32_16x16x32_bf16 v[82:85], v[168:171], v[192:195], v[82:85]
	v_mfma_f32_16x16x32_bf16 v[70:73], v[160:163], v[200:203], v[70:73]
	v_mfma_f32_16x16x32_bf16 v[66:69], v[168:171], v[200:203], v[66:69]
	s_barrier
	s_setprio 0
	ds_read_b128 v[172:175], v133 offset:49152
	ds_read_b128 v[176:179], v133 offset:50176
	s_add_i32 s59, s58, 0x80
	s_mov_b32 m0, s40
	s_nop 0
	buffer_load_dwordx4 v130, s[8:11], s59 offen lds
	ds_read_b128 v[180:183], v133 offset:51200
	ds_read_b128 v[184:187], v133 offset:52224
	s_add_i32 s58, s58, 0xb0080
	s_mov_b32 m0, s41
	s_nop 0
	buffer_load_dwordx4 v131, s[8:11], s59 offen lds
	ds_read_b128 v[188:191], v133 offset:53248
	ds_read_b128 v[192:195], v133 offset:54272
	s_nop 0
	s_mov_b32 m0, s44
	s_nop 0
	buffer_load_dwordx4 v130, s[8:11], s58 offen lds
	ds_read_b128 v[196:199], v133 offset:55296
	ds_read_b128 v[200:203], v133 offset:56320
	s_nop 0
	s_mov_b32 m0, s45
	s_nop 0
	buffer_load_dwordx4 v131, s[8:11], s58 offen lds
	s_nop 0
	s_mov_b32 m0, s42
	s_nop 0
	buffer_load_dwordx4 v130, s[12:15], s55 offen lds
	s_nop 0
	s_mov_b32 m0, s43
	s_nop 0
	buffer_load_dwordx4 v131, s[12:15], s55 offen lds
	s_waitcnt vmcnt(8)
	s_waitcnt lgkmcnt(0)
	s_setprio 1
	s_barrier
	v_mfma_f32_16x16x32_bf16 v[62:65], v[138:141], v[172:175], v[62:65]
	v_mfma_f32_16x16x32_bf16 v[58:61], v[148:151], v[172:175], v[58:61]
	v_mfma_f32_16x16x32_bf16 v[46:49], v[138:141], v[180:183], v[46:49]
	v_mfma_f32_16x16x32_bf16 v[42:45], v[148:151], v[180:183], v[42:45]
	v_mfma_f32_16x16x32_bf16 v[30:33], v[138:141], v[188:191], v[30:33]
	v_mfma_f32_16x16x32_bf16 v[26:29], v[148:151], v[188:191], v[26:29]
	v_mfma_f32_16x16x32_bf16 v[14:17], v[138:141], v[196:199], v[14:17]
	v_mfma_f32_16x16x32_bf16 v[10:13], v[148:151], v[196:199], v[10:13]
	v_mfma_f32_16x16x32_bf16 v[62:65], v[142:145], v[176:179], v[62:65]
	v_mfma_f32_16x16x32_bf16 v[58:61], v[152:155], v[176:179], v[58:61]
	v_mfma_f32_16x16x32_bf16 v[46:49], v[142:145], v[184:187], v[46:49]
	v_mfma_f32_16x16x32_bf16 v[42:45], v[152:155], v[184:187], v[42:45]
	v_mfma_f32_16x16x32_bf16 v[30:33], v[142:145], v[192:195], v[30:33]
	v_mfma_f32_16x16x32_bf16 v[26:29], v[152:155], v[192:195], v[26:29]
	v_mfma_f32_16x16x32_bf16 v[14:17], v[142:145], v[200:203], v[14:17]
	v_mfma_f32_16x16x32_bf16 v[10:13], v[152:155], v[200:203], v[10:13]
	s_setprio 0
	s_setprio 1
	v_mfma_f32_16x16x32_bf16 v[54:57], v[156:159], v[172:175], v[54:57]
	v_mfma_f32_16x16x32_bf16 v[50:53], v[164:167], v[172:175], v[50:53]
	v_mfma_f32_16x16x32_bf16 v[38:41], v[156:159], v[180:183], v[38:41]
	v_mfma_f32_16x16x32_bf16 v[34:37], v[164:167], v[180:183], v[34:37]
	v_mfma_f32_16x16x32_bf16 v[22:25], v[156:159], v[188:191], v[22:25]
	v_mfma_f32_16x16x32_bf16 v[18:21], v[164:167], v[188:191], v[18:21]
	v_mfma_f32_16x16x32_bf16 v[6:9], v[156:159], v[196:199], v[6:9]
	v_mfma_f32_16x16x32_bf16 v[2:5], v[164:167], v[196:199], v[2:5]
	v_mfma_f32_16x16x32_bf16 v[54:57], v[160:163], v[176:179], v[54:57]
	v_mfma_f32_16x16x32_bf16 v[50:53], v[168:171], v[176:179], v[50:53]
	v_mfma_f32_16x16x32_bf16 v[38:41], v[160:163], v[184:187], v[38:41]
	v_mfma_f32_16x16x32_bf16 v[34:37], v[168:171], v[184:187], v[34:37]
	v_mfma_f32_16x16x32_bf16 v[22:25], v[160:163], v[192:195], v[22:25]
	v_mfma_f32_16x16x32_bf16 v[18:21], v[168:171], v[192:195], v[18:21]
	v_mfma_f32_16x16x32_bf16 v[6:9], v[160:163], v[200:203], v[6:9]
	v_mfma_f32_16x16x32_bf16 v[2:5], v[168:171], v[200:203], v[2:5]
	s_barrier
	s_setprio 0
	s_add_i32 s0, s0, 2
	s_addk_i32 s1, 0x100
	s_cmp_gt_u32 s0, 41
	s_cbranch_scc0 .LBB0_467
	s_andn2_b64 vcc, exec, s[6:7]
	s_cbranch_vccnz .LBB0_455
	v_mov_b32_e32 v2, 0
	s_mov_b32 s18, s50
	s_mov_b32 s31, s51
	s_mov_b32 s33, s54
	s_mov_b32 s3, s53
	s_mov_b32 s49, s52
	v_mov_b32_e32 v3, v2
	v_mov_b32_e32 v4, v2
	v_mov_b32_e32 v5, v2
	v_mov_b32_e32 v6, v2
	v_mov_b32_e32 v7, v2
	v_mov_b32_e32 v8, v2
	v_mov_b32_e32 v9, v2
	v_mov_b32_e32 v18, v2
	v_mov_b32_e32 v19, v2
	v_mov_b32_e32 v20, v2
	v_mov_b32_e32 v21, v2
	v_mov_b32_e32 v22, v2
	v_mov_b32_e32 v23, v2
	v_mov_b32_e32 v24, v2
	v_mov_b32_e32 v25, v2
	v_mov_b32_e32 v34, v2
	v_mov_b32_e32 v35, v2
	v_mov_b32_e32 v36, v2
	v_mov_b32_e32 v37, v2
	v_mov_b32_e32 v38, v2
	v_mov_b32_e32 v39, v2
	v_mov_b32_e32 v40, v2
	v_mov_b32_e32 v41, v2
	v_mov_b32_e32 v50, v2
	v_mov_b32_e32 v51, v2
	v_mov_b32_e32 v52, v2
	v_mov_b32_e32 v53, v2
	v_mov_b32_e32 v54, v2
	v_mov_b32_e32 v55, v2
	v_mov_b32_e32 v56, v2
	v_mov_b32_e32 v57, v2
	v_mov_b32_e32 v10, v2
	v_mov_b32_e32 v11, v2
	v_mov_b32_e32 v12, v2
	v_mov_b32_e32 v13, v2
	v_mov_b32_e32 v14, v2
	v_mov_b32_e32 v15, v2
	v_mov_b32_e32 v16, v2
	v_mov_b32_e32 v17, v2
	v_mov_b32_e32 v26, v2
	v_mov_b32_e32 v27, v2
	v_mov_b32_e32 v28, v2
	v_mov_b32_e32 v29, v2
	v_mov_b32_e32 v30, v2
	v_mov_b32_e32 v31, v2
	v_mov_b32_e32 v32, v2
	v_mov_b32_e32 v33, v2
	v_mov_b32_e32 v42, v2
	v_mov_b32_e32 v43, v2
	v_mov_b32_e32 v44, v2
	v_mov_b32_e32 v45, v2
	v_mov_b32_e32 v46, v2
	v_mov_b32_e32 v47, v2
	v_mov_b32_e32 v48, v2
	v_mov_b32_e32 v49, v2
	v_mov_b32_e32 v58, v2
	v_mov_b32_e32 v59, v2
	v_mov_b32_e32 v60, v2
	v_mov_b32_e32 v61, v2
	v_mov_b32_e32 v62, v2
	v_mov_b32_e32 v63, v2
	v_mov_b32_e32 v64, v2
	v_mov_b32_e32 v65, v2
	v_mov_b32_e32 v66, v2
	v_mov_b32_e32 v67, v2
	v_mov_b32_e32 v68, v2
	v_mov_b32_e32 v69, v2
	v_mov_b32_e32 v70, v2
	v_mov_b32_e32 v71, v2
	v_mov_b32_e32 v72, v2
	v_mov_b32_e32 v73, v2
	v_mov_b32_e32 v82, v2
	v_mov_b32_e32 v83, v2
	v_mov_b32_e32 v84, v2
	v_mov_b32_e32 v85, v2
	v_mov_b32_e32 v86, v2
	v_mov_b32_e32 v87, v2
	v_mov_b32_e32 v88, v2
	v_mov_b32_e32 v89, v2
	v_mov_b32_e32 v98, v2
	v_mov_b32_e32 v99, v2
	v_mov_b32_e32 v100, v2
	v_mov_b32_e32 v101, v2
	v_mov_b32_e32 v102, v2
	v_mov_b32_e32 v103, v2
	v_mov_b32_e32 v104, v2
	v_mov_b32_e32 v105, v2
	v_mov_b32_e32 v114, v2
	v_mov_b32_e32 v115, v2
	v_mov_b32_e32 v116, v2
	v_mov_b32_e32 v117, v2
	v_mov_b32_e32 v118, v2
	v_mov_b32_e32 v119, v2
	v_mov_b32_e32 v120, v2
	v_mov_b32_e32 v121, v2
	v_mov_b32_e32 v74, v2
	v_mov_b32_e32 v75, v2
	v_mov_b32_e32 v76, v2
	v_mov_b32_e32 v77, v2
	v_mov_b32_e32 v78, v2
	v_mov_b32_e32 v79, v2
	v_mov_b32_e32 v80, v2
	v_mov_b32_e32 v81, v2
	v_mov_b32_e32 v90, v2
	v_mov_b32_e32 v91, v2
	v_mov_b32_e32 v92, v2
	v_mov_b32_e32 v93, v2
	v_mov_b32_e32 v94, v2
	v_mov_b32_e32 v95, v2
	v_mov_b32_e32 v96, v2
	v_mov_b32_e32 v97, v2
	v_mov_b32_e32 v106, v2
	v_mov_b32_e32 v107, v2
	v_mov_b32_e32 v108, v2
	v_mov_b32_e32 v109, v2
	v_mov_b32_e32 v110, v2
	v_mov_b32_e32 v111, v2
	v_mov_b32_e32 v112, v2
	v_mov_b32_e32 v113, v2
	v_mov_b32_e32 v122, v2
	v_mov_b32_e32 v123, v2
	v_mov_b32_e32 v124, v2
	v_mov_b32_e32 v125, v2
	v_mov_b32_e32 v134, v2
	v_mov_b32_e32 v135, v2
	v_mov_b32_e32 v136, v2
	v_mov_b32_e32 v137, v2
	s_branch .LBB0_455

.LBB0_619:
	ds_read_b128 v[38:41], v210
	ds_read_b128 v[42:45], v210 offset:1024
	ds_read_b128 v[46:49], v210 offset:2048
	ds_read_b128 v[58:61], v210 offset:3072
	ds_read_b128 v[142:145], v211
	ds_read_b128 v[146:149], v211 offset:1024
	ds_read_b128 v[150:153], v211 offset:2048
	ds_read_b128 v[154:157], v211 offset:3072
	s_add_i32 s6, s1, 0xfffe0080
	s_cmp_eq_u32 s3, 4
	s_cselect_b32 s8, s75, s6
	s_cselect_b32 s7, s0, s2
	s_add_i32 s6, s8, 0x80
	s_mov_b32 m0, s68
	s_nop 0
	buffer_load_dwordx4 v206, s[16:19], s1 offen lds
	s_nop 0
	s_mov_b32 m0, s69
	s_nop 0
	buffer_load_dwordx4 v207, s[16:19], s1 offen lds
	ds_read_b128 v[166:169], v212
	ds_read_b128 v[170:173], v212 offset:1024
	ds_read_b128 v[174:177], v212 offset:2048
	ds_read_b128 v[178:181], v212 offset:3072
	ds_read_b128 v[190:193], v212 offset:4096
	ds_read_b128 v[194:197], v212 offset:5120
	ds_read_b128 v[198:201], v212 offset:6144
	ds_read_b128 v[216:219], v212 offset:7168
	s_waitcnt vmcnt(8)
	s_waitcnt lgkmcnt(0)
	s_setprio 1
	s_barrier
	v_mfma_i32_16x16x64_i8 v[162:165], v[38:41], v[166:169], v[162:165]
	v_mfma_i32_16x16x64_i8 v[158:161], v[46:49], v[166:169], v[158:161]
	v_mfma_i32_16x16x64_i8 v[130:133], v[38:41], v[174:177], v[130:133]
	v_mfma_i32_16x16x64_i8 v[126:129], v[46:49], v[174:177], v[126:129]
	v_mfma_i32_16x16x64_i8 v[114:117], v[38:41], v[190:193], v[114:117]
	v_mfma_i32_16x16x64_i8 v[110:113], v[46:49], v[190:193], v[110:113]
	v_mfma_i32_16x16x64_i8 v[98:101], v[38:41], v[198:201], v[98:101]
	v_mfma_i32_16x16x64_i8 v[94:97], v[46:49], v[198:201], v[94:97]
	v_mfma_i32_16x16x64_i8 v[162:165], v[42:45], v[170:173], v[162:165]
	v_mfma_i32_16x16x64_i8 v[158:161], v[58:61], v[170:173], v[158:161]
	v_mfma_i32_16x16x64_i8 v[130:133], v[42:45], v[178:181], v[130:133]
	v_mfma_i32_16x16x64_i8 v[126:129], v[58:61], v[178:181], v[126:129]
	v_mfma_i32_16x16x64_i8 v[114:117], v[42:45], v[194:197], v[114:117]
	v_mfma_i32_16x16x64_i8 v[110:113], v[58:61], v[194:197], v[110:113]
	v_mfma_i32_16x16x64_i8 v[98:101], v[42:45], v[216:219], v[98:101]
	v_mfma_i32_16x16x64_i8 v[94:97], v[58:61], v[216:219], v[94:97]
	s_setprio 0
	s_setprio 1
	v_mfma_i32_16x16x64_i8 v[138:141], v[142:145], v[166:169], v[138:141]
	v_mfma_i32_16x16x64_i8 v[134:137], v[150:153], v[166:169], v[134:137]
	v_mfma_i32_16x16x64_i8 v[122:125], v[142:145], v[174:177], v[122:125]
	v_mfma_i32_16x16x64_i8 v[118:121], v[150:153], v[174:177], v[118:121]
	v_mfma_i32_16x16x64_i8 v[106:109], v[142:145], v[190:193], v[106:109]
	v_mfma_i32_16x16x64_i8 v[102:105], v[150:153], v[190:193], v[102:105]
	v_mfma_i32_16x16x64_i8 v[90:93], v[142:145], v[198:201], v[90:93]
	v_mfma_i32_16x16x64_i8 v[86:89], v[150:153], v[198:201], v[86:89]
	v_mfma_i32_16x16x64_i8 v[138:141], v[146:149], v[170:173], v[138:141]
	v_mfma_i32_16x16x64_i8 v[134:137], v[154:157], v[170:173], v[134:137]
	v_mfma_i32_16x16x64_i8 v[122:125], v[146:149], v[178:181], v[122:125]
	v_mfma_i32_16x16x64_i8 v[118:121], v[154:157], v[178:181], v[118:121]
	v_mfma_i32_16x16x64_i8 v[106:109], v[146:149], v[194:197], v[106:109]
	v_mfma_i32_16x16x64_i8 v[102:105], v[154:157], v[194:197], v[102:105]
	v_mfma_i32_16x16x64_i8 v[90:93], v[146:149], v[216:219], v[90:93]
	v_mfma_i32_16x16x64_i8 v[86:89], v[154:157], v[216:219], v[86:89]
	s_barrier
	s_setprio 0
	ds_read_b128 v[166:169], v212 offset:16384
	ds_read_b128 v[170:173], v212 offset:17408
	s_mov_b32 m0, s48
	s_nop 0
	buffer_load_dwordx4 v204, s[12:15], s7 offen lds
	ds_read_b128 v[174:177], v212 offset:18432
	ds_read_b128 v[178:181], v212 offset:19456
	s_add_i32 s9, s7, 0x20000
	s_mov_b32 m0, s49
	s_nop 0
	buffer_load_dwordx4 v205, s[12:15], s7 offen lds
	ds_read_b128 v[190:193], v212 offset:20480
	ds_read_b128 v[194:197], v212 offset:21504
	s_nop 0
	s_mov_b32 m0, s50
	s_nop 0
	buffer_load_dwordx4 v204, s[12:15], s9 offen lds
	ds_read_b128 v[198:201], v212 offset:22528
	ds_read_b128 v[216:219], v212 offset:23552
	s_nop 0
	s_mov_b32 m0, s51
	s_nop 0
	buffer_load_dwordx4 v205, s[12:15], s9 offen lds
	s_nop 0
	s_mov_b32 m0, s47
	s_nop 0
	buffer_load_dwordx4 v206, s[16:19], s8 offen lds
	s_nop 0
	s_mov_b32 m0, s52
	s_nop 0
	buffer_load_dwordx4 v207, s[16:19], s8 offen lds
	s_waitcnt vmcnt(8)
	s_waitcnt lgkmcnt(0)
	s_setprio 1
	s_barrier
	v_mfma_i32_16x16x64_i8 v[82:85], v[38:41], v[166:169], v[82:85]
	v_mfma_i32_16x16x64_i8 v[78:81], v[46:49], v[166:169], v[78:81]
	v_mfma_i32_16x16x64_i8 v[66:69], v[38:41], v[174:177], v[66:69]
	v_mfma_i32_16x16x64_i8 v[62:65], v[46:49], v[174:177], v[62:65]
	v_mfma_i32_16x16x64_i8 v[34:37], v[38:41], v[190:193], v[34:37]
	v_mfma_i32_16x16x64_i8 v[30:33], v[46:49], v[190:193], v[30:33]
	v_mfma_i32_16x16x64_i8 v[18:21], v[38:41], v[198:201], v[18:21]
	v_mfma_i32_16x16x64_i8 v[14:17], v[46:49], v[198:201], v[14:17]
	v_mfma_i32_16x16x64_i8 v[82:85], v[42:45], v[170:173], v[82:85]
	v_mfma_i32_16x16x64_i8 v[78:81], v[58:61], v[170:173], v[78:81]
	v_mfma_i32_16x16x64_i8 v[66:69], v[42:45], v[178:181], v[66:69]
	v_mfma_i32_16x16x64_i8 v[62:65], v[58:61], v[178:181], v[62:65]
	v_mfma_i32_16x16x64_i8 v[34:37], v[42:45], v[194:197], v[34:37]
	v_mfma_i32_16x16x64_i8 v[30:33], v[58:61], v[194:197], v[30:33]
	v_mfma_i32_16x16x64_i8 v[18:21], v[42:45], v[216:219], v[18:21]
	v_mfma_i32_16x16x64_i8 v[14:17], v[58:61], v[216:219], v[14:17]
	s_setprio 0
	s_setprio 1
	v_mfma_i32_16x16x64_i8 v[50:53], v[150:153], v[174:177], v[50:53]
	v_mfma_i32_16x16x64_i8 v[26:29], v[142:145], v[190:193], v[26:29]
	v_mfma_i32_16x16x64_i8 v[22:25], v[150:153], v[190:193], v[22:25]
	v_mfma_i32_16x16x64_i8 v[10:13], v[142:145], v[198:201], v[10:13]
	v_mfma_i32_16x16x64_i8 v[4:7], v[150:153], v[198:201], v[6:9]
	v_mfma_i32_16x16x64_i8 v[38:41], v[142:145], v[166:169], v[74:77]
	v_mfma_i32_16x16x64_i8 v[42:45], v[150:153], v[166:169], v[70:73]
	v_mfma_i32_16x16x64_i8 v[46:49], v[142:145], v[174:177], v[54:57]
	v_mfma_i32_16x16x64_i8 v[50:53], v[154:157], v[178:181], v[50:53]
	v_mfma_i32_16x16x64_i8 v[26:29], v[146:149], v[194:197], v[26:29]
	v_mfma_i32_16x16x64_i8 v[22:25], v[154:157], v[194:197], v[22:25]
	v_mfma_i32_16x16x64_i8 v[10:13], v[146:149], v[216:219], v[10:13]
	v_mfma_i32_16x16x64_i8 v[4:7], v[154:157], v[216:219], v[4:7]
	v_mfma_i32_16x16x64_i8 v[38:41], v[146:149], v[170:173], v[38:41]
	v_mfma_i32_16x16x64_i8 v[42:45], v[154:157], v[170:173], v[42:45]
	v_mfma_i32_16x16x64_i8 v[46:49], v[146:149], v[178:181], v[46:49]
	s_barrier
	s_setprio 0
	ds_read_b128 v[54:57], v213
	ds_read_b128 v[58:61], v213 offset:1024
	ds_read_b128 v[70:73], v213 offset:2048
	ds_read_b128 v[74:77], v213 offset:3072
	ds_read_b128 v[142:145], v214
	ds_read_b128 v[146:149], v214 offset:1024
	ds_read_b128 v[150:153], v214 offset:2048
	ds_read_b128 v[154:157], v214 offset:3072
	s_add_i32 s8, s8, 0x20000
	s_mov_b32 m0, s53
	s_nop 0
	buffer_load_dwordx4 v206, s[16:19], s8 offen lds
	s_nop 0
	s_mov_b32 m0, s54
	s_nop 0
	buffer_load_dwordx4 v207, s[16:19], s8 offen lds
	ds_read_b128 v[166:169], v212 offset:32768
	ds_read_b128 v[170:173], v212 offset:33792
	ds_read_b128 v[174:177], v212 offset:34816
	ds_read_b128 v[178:181], v212 offset:35840
	ds_read_b128 v[190:193], v212 offset:36864
	ds_read_b128 v[194:197], v212 offset:37888
	ds_read_b128 v[198:201], v212 offset:38912
	ds_read_b128 v[216:219], v212 offset:39936
	s_waitcnt vmcnt(8)
	s_waitcnt lgkmcnt(0)
	s_setprio 1
	s_barrier
	v_mfma_i32_16x16x64_i8 v[162:165], v[54:57], v[166:169], v[162:165]
	v_mfma_i32_16x16x64_i8 v[158:161], v[70:73], v[166:169], v[158:161]
	v_mfma_i32_16x16x64_i8 v[130:133], v[54:57], v[174:177], v[130:133]
	v_mfma_i32_16x16x64_i8 v[126:129], v[70:73], v[174:177], v[126:129]
	v_mfma_i32_16x16x64_i8 v[114:117], v[54:57], v[190:193], v[114:117]
	v_mfma_i32_16x16x64_i8 v[110:113], v[70:73], v[190:193], v[110:113]
	v_mfma_i32_16x16x64_i8 v[98:101], v[54:57], v[198:201], v[98:101]
	v_mfma_i32_16x16x64_i8 v[94:97], v[70:73], v[198:201], v[94:97]
	v_mfma_i32_16x16x64_i8 v[162:165], v[58:61], v[170:173], v[162:165]
	v_mfma_i32_16x16x64_i8 v[158:161], v[74:77], v[170:173], v[158:161]
	v_mfma_i32_16x16x64_i8 v[130:133], v[58:61], v[178:181], v[130:133]
	v_mfma_i32_16x16x64_i8 v[126:129], v[74:77], v[178:181], v[126:129]
	v_mfma_i32_16x16x64_i8 v[114:117], v[58:61], v[194:197], v[114:117]
	v_mfma_i32_16x16x64_i8 v[110:113], v[74:77], v[194:197], v[110:113]
	v_mfma_i32_16x16x64_i8 v[98:101], v[58:61], v[216:219], v[98:101]
	v_mfma_i32_16x16x64_i8 v[94:97], v[74:77], v[216:219], v[94:97]
	s_setprio 0
	s_setprio 1
	v_mfma_i32_16x16x64_i8 v[138:141], v[142:145], v[166:169], v[138:141]
	v_mfma_i32_16x16x64_i8 v[134:137], v[150:153], v[166:169], v[134:137]
	v_mfma_i32_16x16x64_i8 v[122:125], v[142:145], v[174:177], v[122:125]
	v_mfma_i32_16x16x64_i8 v[118:121], v[150:153], v[174:177], v[118:121]
	v_mfma_i32_16x16x64_i8 v[106:109], v[142:145], v[190:193], v[106:109]
	v_mfma_i32_16x16x64_i8 v[102:105], v[150:153], v[190:193], v[102:105]
	v_mfma_i32_16x16x64_i8 v[90:93], v[142:145], v[198:201], v[90:93]
	v_mfma_i32_16x16x64_i8 v[86:89], v[150:153], v[198:201], v[86:89]
	v_mfma_i32_16x16x64_i8 v[138:141], v[146:149], v[170:173], v[138:141]
	v_mfma_i32_16x16x64_i8 v[134:137], v[154:157], v[170:173], v[134:137]
	v_mfma_i32_16x16x64_i8 v[122:125], v[146:149], v[178:181], v[122:125]
	v_mfma_i32_16x16x64_i8 v[118:121], v[154:157], v[178:181], v[118:121]
	v_mfma_i32_16x16x64_i8 v[106:109], v[146:149], v[194:197], v[106:109]
	v_mfma_i32_16x16x64_i8 v[102:105], v[154:157], v[194:197], v[102:105]
	v_mfma_i32_16x16x64_i8 v[90:93], v[146:149], v[216:219], v[90:93]
	v_mfma_i32_16x16x64_i8 v[86:89], v[154:157], v[216:219], v[86:89]
	s_barrier
	s_setprio 0
	ds_read_b128 v[166:169], v212 offset:49152
	ds_read_b128 v[170:173], v212 offset:50176
	s_or_b32 s8, s7, 0x80
	s_mov_b32 m0, s62
	s_nop 0
	buffer_load_dwordx4 v204, s[12:15], s8 offen lds
	ds_read_b128 v[174:177], v212 offset:51200
	ds_read_b128 v[178:181], v212 offset:52224
	s_add_i32 s7, s7, 0x20080
	s_mov_b32 m0, s63
	s_nop 0
	buffer_load_dwordx4 v205, s[12:15], s8 offen lds
	ds_read_b128 v[190:193], v212 offset:53248
	ds_read_b128 v[194:197], v212 offset:54272
	s_nop 0
	s_mov_b32 m0, s66
	s_nop 0
	buffer_load_dwordx4 v204, s[12:15], s7 offen lds
	ds_read_b128 v[198:201], v212 offset:55296
	ds_read_b128 v[216:219], v212 offset:56320
	s_nop 0
	s_mov_b32 m0, s67
	s_nop 0
	buffer_load_dwordx4 v205, s[12:15], s7 offen lds
	s_nop 0
	s_mov_b32 m0, s64
	s_nop 0
	buffer_load_dwordx4 v206, s[16:19], s6 offen lds
	s_nop 0
	s_mov_b32 m0, s65
	s_nop 0
	buffer_load_dwordx4 v207, s[16:19], s6 offen lds
	s_waitcnt vmcnt(8)
	s_waitcnt lgkmcnt(0)
	s_setprio 1
	s_barrier
	v_mfma_i32_16x16x64_i8 v[82:85], v[54:57], v[166:169], v[82:85]
	v_mfma_i32_16x16x64_i8 v[78:81], v[70:73], v[166:169], v[78:81]
	v_mfma_i32_16x16x64_i8 v[66:69], v[54:57], v[174:177], v[66:69]
	v_mfma_i32_16x16x64_i8 v[62:65], v[70:73], v[174:177], v[62:65]
	v_mfma_i32_16x16x64_i8 v[34:37], v[54:57], v[190:193], v[34:37]
	v_mfma_i32_16x16x64_i8 v[30:33], v[70:73], v[190:193], v[30:33]
	v_mfma_i32_16x16x64_i8 v[18:21], v[54:57], v[198:201], v[18:21]
	v_mfma_i32_16x16x64_i8 v[14:17], v[70:73], v[198:201], v[14:17]
	v_mfma_i32_16x16x64_i8 v[82:85], v[58:61], v[170:173], v[82:85]
	v_mfma_i32_16x16x64_i8 v[78:81], v[74:77], v[170:173], v[78:81]
	v_mfma_i32_16x16x64_i8 v[66:69], v[58:61], v[178:181], v[66:69]
	v_mfma_i32_16x16x64_i8 v[62:65], v[74:77], v[178:181], v[62:65]
	v_mfma_i32_16x16x64_i8 v[34:37], v[58:61], v[194:197], v[34:37]
	v_mfma_i32_16x16x64_i8 v[30:33], v[74:77], v[194:197], v[30:33]
	v_mfma_i32_16x16x64_i8 v[18:21], v[58:61], v[216:219], v[18:21]
	v_mfma_i32_16x16x64_i8 v[14:17], v[74:77], v[216:219], v[14:17]
	s_setprio 0
	s_setprio 1
	v_mfma_i32_16x16x64_i8 v[38:41], v[142:145], v[166:169], v[38:41]
	v_mfma_i32_16x16x64_i8 v[74:77], v[146:149], v[170:173], v[38:41]
	v_mfma_i32_16x16x64_i8 v[38:41], v[150:153], v[166:169], v[42:45]
	v_mfma_i32_16x16x64_i8 v[70:73], v[154:157], v[170:173], v[38:41]
	v_mfma_i32_16x16x64_i8 v[38:41], v[142:145], v[174:177], v[46:49]
	v_mfma_i32_16x16x64_i8 v[54:57], v[146:149], v[178:181], v[38:41]
	v_mfma_i32_16x16x64_i8 v[38:41], v[150:153], v[174:177], v[50:53]
	v_mfma_i32_16x16x64_i8 v[26:29], v[142:145], v[190:193], v[26:29]
	v_mfma_i32_16x16x64_i8 v[22:25], v[150:153], v[190:193], v[22:25]
	v_mfma_i32_16x16x64_i8 v[8:11], v[142:145], v[198:201], v[10:13]
	v_mfma_i32_16x16x64_i8 v[4:7], v[150:153], v[198:201], v[4:7]
	v_mfma_i32_16x16x64_i8 v[50:53], v[154:157], v[178:181], v[38:41]
	v_mfma_i32_16x16x64_i8 v[26:29], v[146:149], v[194:197], v[26:29]
	v_mfma_i32_16x16x64_i8 v[22:25], v[154:157], v[194:197], v[22:25]
	v_mfma_i32_16x16x64_i8 v[10:13], v[146:149], v[216:219], v[8:11]
	v_mfma_i32_16x16x64_i8 v[6:9], v[154:157], v[216:219], v[4:7]
	s_barrier
	s_setprio 0
	s_add_i32 s3, s3, 2
	s_addk_i32 s1, 0x100
	s_addk_i32 s2, 0x100
	s_cmp_gt_u32 s3, 5
	s_cbranch_scc0 .LBB0_619
	s_and_b64 vcc, exec, s[34:35]
	s_cbranch_vccz .LBB0_622
	s_barrier

.LBB0_943:
	v_add_u32_e32 v150, 0x10000, v8
	v_add_u32_e32 v166, 0x14000, v8
	ds_read_b128 v[10:13], v150
	ds_read_b128 v[14:17], v150 offset:1024
	ds_read_b128 v[146:149], v150 offset:2048
	ds_read_b128 v[150:153], v150 offset:3072
	ds_read_b128 v[154:157], v166
	ds_read_b128 v[158:161], v166 offset:1024
	ds_read_b128 v[162:165], v166 offset:2048
	ds_read_b128 v[166:169], v166 offset:3072
	s_add_i32 s61, s37, s58
	s_add_i32 s60, s33, s58
	s_add_i32 s59, s61, 0x400
	s_addk_i32 s60, 0x400
	s_cmp_eq_u32 s58, 0
	s_cselect_b32 s62, s53, s59
	s_cselect_b32 s60, s54, s60
	s_or_b32 s59, s62, 0x80
	s_add_i32 s61, s61, 0x20380
	s_mov_b32 m0, s48
	s_nop 0
	buffer_load_dwordx4 v6, s[12:15], s61 offen lds
	s_nop 0
	s_mov_b32 m0, s49
	s_nop 0
	buffer_load_dwordx4 v7, s[12:15], s61 offen lds
	ds_read_b128 v[170:173], v9
	ds_read_b128 v[174:177], v9 offset:1024
	ds_read_b128 v[178:181], v9 offset:2048
	ds_read_b128 v[182:185], v9 offset:3072
	ds_read_b128 v[186:189], v9 offset:4096
	ds_read_b128 v[190:193], v9 offset:5120
	ds_read_b128 v[194:197], v9 offset:6144
	ds_read_b128 v[198:201], v9 offset:7168
	s_waitcnt vmcnt(8)
	s_waitcnt lgkmcnt(0)
	s_setprio 1
	s_barrier
	v_mfma_i32_16x16x64_i8 v[142:145], v[10:13], v[170:173], v[142:145]
	v_mfma_i32_16x16x64_i8 v[138:141], v[146:149], v[170:173], v[138:141]
	v_mfma_i32_16x16x64_i8 v[126:129], v[10:13], v[178:181], v[126:129]
	v_mfma_i32_16x16x64_i8 v[122:125], v[146:149], v[178:181], v[122:125]
	v_mfma_i32_16x16x64_i8 v[110:113], v[10:13], v[186:189], v[110:113]
	v_mfma_i32_16x16x64_i8 v[106:109], v[146:149], v[186:189], v[106:109]
	v_mfma_i32_16x16x64_i8 v[94:97], v[10:13], v[194:197], v[94:97]
	v_mfma_i32_16x16x64_i8 v[90:93], v[146:149], v[194:197], v[90:93]
	v_mfma_i32_16x16x64_i8 v[142:145], v[14:17], v[174:177], v[142:145]
	v_mfma_i32_16x16x64_i8 v[138:141], v[150:153], v[174:177], v[138:141]
	v_mfma_i32_16x16x64_i8 v[126:129], v[14:17], v[182:185], v[126:129]
	v_mfma_i32_16x16x64_i8 v[122:125], v[150:153], v[182:185], v[122:125]
	v_mfma_i32_16x16x64_i8 v[110:113], v[14:17], v[190:193], v[110:113]
	v_mfma_i32_16x16x64_i8 v[106:109], v[150:153], v[190:193], v[106:109]
	v_mfma_i32_16x16x64_i8 v[94:97], v[14:17], v[198:201], v[94:97]
	v_mfma_i32_16x16x64_i8 v[90:93], v[150:153], v[198:201], v[90:93]
	s_setprio 0
	s_setprio 1
	v_mfma_i32_16x16x64_i8 v[134:137], v[154:157], v[170:173], v[134:137]
	v_mfma_i32_16x16x64_i8 v[130:133], v[162:165], v[170:173], v[130:133]
	v_mfma_i32_16x16x64_i8 v[118:121], v[154:157], v[178:181], v[118:121]
	v_mfma_i32_16x16x64_i8 v[114:117], v[162:165], v[178:181], v[114:117]
	v_mfma_i32_16x16x64_i8 v[102:105], v[154:157], v[186:189], v[102:105]
	v_mfma_i32_16x16x64_i8 v[98:101], v[162:165], v[186:189], v[98:101]
	v_mfma_i32_16x16x64_i8 v[86:89], v[154:157], v[194:197], v[86:89]
	v_mfma_i32_16x16x64_i8 v[82:85], v[162:165], v[194:197], v[82:85]
	v_mfma_i32_16x16x64_i8 v[134:137], v[158:161], v[174:177], v[134:137]
	v_mfma_i32_16x16x64_i8 v[130:133], v[166:169], v[174:177], v[130:133]
	v_mfma_i32_16x16x64_i8 v[118:121], v[158:161], v[182:185], v[118:121]
	v_mfma_i32_16x16x64_i8 v[114:117], v[166:169], v[182:185], v[114:117]
	v_mfma_i32_16x16x64_i8 v[102:105], v[158:161], v[190:193], v[102:105]
	v_mfma_i32_16x16x64_i8 v[98:101], v[166:169], v[190:193], v[98:101]
	v_mfma_i32_16x16x64_i8 v[86:89], v[158:161], v[198:201], v[86:89]
	v_mfma_i32_16x16x64_i8 v[82:85], v[166:169], v[198:201], v[82:85]
	s_barrier
	s_setprio 0
	ds_read_b128 v[170:173], v9 offset:16384
	ds_read_b128 v[174:177], v9 offset:17408
	s_mov_b32 m0, s29
	s_nop 0
	buffer_load_dwordx4 v6, s[8:11], s60 offen lds
	ds_read_b128 v[178:181], v9 offset:18432
	ds_read_b128 v[182:185], v9 offset:19456
	s_add_i32 s61, s60, 0x20000
	s_mov_b32 m0, s34
	s_nop 0
	buffer_load_dwordx4 v7, s[8:11], s60 offen lds
	ds_read_b128 v[186:189], v9 offset:20480
	ds_read_b128 v[190:193], v9 offset:21504
	s_nop 0
	s_mov_b32 m0, s35
	s_nop 0
	buffer_load_dwordx4 v6, s[8:11], s61 offen lds
	ds_read_b128 v[194:197], v9 offset:22528
	ds_read_b128 v[198:201], v9 offset:23552
	s_nop 0
	s_mov_b32 m0, s36
	s_nop 0
	buffer_load_dwordx4 v7, s[8:11], s61 offen lds
	s_nop 0
	s_mov_b32 m0, s28
	s_nop 0
	buffer_load_dwordx4 v6, s[12:15], s62 offen lds
	s_nop 0
	s_mov_b32 m0, s38
	s_nop 0
	buffer_load_dwordx4 v7, s[12:15], s62 offen lds
	s_waitcnt vmcnt(8)
	s_waitcnt lgkmcnt(0)
	s_setprio 1
	s_barrier
	v_mfma_i32_16x16x64_i8 v[78:81], v[10:13], v[170:173], v[78:81]
	v_mfma_i32_16x16x64_i8 v[74:77], v[146:149], v[170:173], v[74:77]
	v_mfma_i32_16x16x64_i8 v[62:65], v[10:13], v[178:181], v[62:65]
	v_mfma_i32_16x16x64_i8 v[58:61], v[146:149], v[178:181], v[58:61]
	v_mfma_i32_16x16x64_i8 v[46:49], v[10:13], v[186:189], v[46:49]
	v_mfma_i32_16x16x64_i8 v[42:45], v[146:149], v[186:189], v[42:45]
	v_mfma_i32_16x16x64_i8 v[10:13], v[10:13], v[194:197], v[30:33]
	v_mfma_i32_16x16x64_i8 v[78:81], v[14:17], v[174:177], v[78:81]
	v_mfma_i32_16x16x64_i8 v[74:77], v[150:153], v[174:177], v[74:77]
	v_mfma_i32_16x16x64_i8 v[62:65], v[14:17], v[182:185], v[62:65]
	v_mfma_i32_16x16x64_i8 v[58:61], v[150:153], v[182:185], v[58:61]
	v_mfma_i32_16x16x64_i8 v[46:49], v[14:17], v[190:193], v[46:49]
	v_mfma_i32_16x16x64_i8 v[42:45], v[150:153], v[190:193], v[42:45]
	v_mfma_i32_16x16x64_i8 v[10:13], v[14:17], v[198:201], v[10:13]
	v_mfma_i32_16x16x64_i8 v[14:17], v[146:149], v[194:197], v[26:29]
	v_mfma_i32_16x16x64_i8 v[14:17], v[150:153], v[198:201], v[14:17]
	s_setprio 0
	s_setprio 1
	v_mfma_i32_16x16x64_i8 v[26:29], v[154:157], v[170:173], v[70:73]
	v_mfma_i32_16x16x64_i8 v[70:73], v[158:161], v[174:177], v[26:29]
	v_mfma_i32_16x16x64_i8 v[26:29], v[162:165], v[170:173], v[66:69]
	v_mfma_i32_16x16x64_i8 v[66:69], v[166:169], v[174:177], v[26:29]
	v_mfma_i32_16x16x64_i8 v[26:29], v[154:157], v[178:181], v[54:57]
	v_mfma_i32_16x16x64_i8 v[54:57], v[158:161], v[182:185], v[26:29]
	v_mfma_i32_16x16x64_i8 v[26:29], v[162:165], v[178:181], v[50:53]
	v_mfma_i32_16x16x64_i8 v[50:53], v[166:169], v[182:185], v[26:29]
	v_mfma_i32_16x16x64_i8 v[26:29], v[154:157], v[186:189], v[38:41]
	v_mfma_i32_16x16x64_i8 v[38:41], v[158:161], v[190:193], v[26:29]
	v_mfma_i32_16x16x64_i8 v[26:29], v[162:165], v[186:189], v[34:37]
	v_mfma_i32_16x16x64_i8 v[22:25], v[154:157], v[194:197], v[22:25]
	v_mfma_i32_16x16x64_i8 v[18:21], v[162:165], v[194:197], v[18:21]
	v_mfma_i32_16x16x64_i8 v[34:37], v[166:169], v[190:193], v[26:29]
	v_mfma_i32_16x16x64_i8 v[22:25], v[158:161], v[198:201], v[22:25]
	v_mfma_i32_16x16x64_i8 v[18:21], v[166:169], v[198:201], v[18:21]
	s_barrier
	s_setprio 0
	v_add_u32_e32 v150, 0x18000, v8
	v_add_u32_e32 v166, 0x1c000, v8
	ds_read_b128 v[26:29], v150
	ds_read_b128 v[30:33], v150 offset:1024
	ds_read_b128 v[146:149], v150 offset:2048
	ds_read_b128 v[150:153], v150 offset:3072
	ds_read_b128 v[154:157], v166
	ds_read_b128 v[158:161], v166 offset:1024
	ds_read_b128 v[162:165], v166 offset:2048
	ds_read_b128 v[166:169], v166 offset:3072
	s_add_i32 s61, s62, 0x20000
	s_mov_b32 m0, s40
	s_nop 0
	buffer_load_dwordx4 v6, s[12:15], s61 offen lds
	s_nop 0
	s_mov_b32 m0, s41
	s_nop 0
	buffer_load_dwordx4 v7, s[12:15], s61 offen lds
	ds_read_b128 v[170:173], v9 offset:32768
	ds_read_b128 v[174:177], v9 offset:33792
	ds_read_b128 v[178:181], v9 offset:34816
	ds_read_b128 v[182:185], v9 offset:35840
	ds_read_b128 v[186:189], v9 offset:36864
	ds_read_b128 v[190:193], v9 offset:37888
	ds_read_b128 v[194:197], v9 offset:38912
	ds_read_b128 v[198:201], v9 offset:39936
	s_waitcnt vmcnt(8)
	s_waitcnt lgkmcnt(0)
	s_setprio 1
	s_barrier
	v_mfma_i32_16x16x64_i8 v[142:145], v[26:29], v[170:173], v[142:145]
	v_mfma_i32_16x16x64_i8 v[138:141], v[146:149], v[170:173], v[138:141]
	v_mfma_i32_16x16x64_i8 v[126:129], v[26:29], v[178:181], v[126:129]
	v_mfma_i32_16x16x64_i8 v[122:125], v[146:149], v[178:181], v[122:125]
	v_mfma_i32_16x16x64_i8 v[110:113], v[26:29], v[186:189], v[110:113]
	v_mfma_i32_16x16x64_i8 v[106:109], v[146:149], v[186:189], v[106:109]
	v_mfma_i32_16x16x64_i8 v[94:97], v[26:29], v[194:197], v[94:97]
	v_mfma_i32_16x16x64_i8 v[90:93], v[146:149], v[194:197], v[90:93]
	v_mfma_i32_16x16x64_i8 v[142:145], v[30:33], v[174:177], v[142:145]
	v_mfma_i32_16x16x64_i8 v[138:141], v[150:153], v[174:177], v[138:141]
	v_mfma_i32_16x16x64_i8 v[126:129], v[30:33], v[182:185], v[126:129]
	v_mfma_i32_16x16x64_i8 v[122:125], v[150:153], v[182:185], v[122:125]
	v_mfma_i32_16x16x64_i8 v[110:113], v[30:33], v[190:193], v[110:113]
	v_mfma_i32_16x16x64_i8 v[106:109], v[150:153], v[190:193], v[106:109]
	v_mfma_i32_16x16x64_i8 v[94:97], v[30:33], v[198:201], v[94:97]
	v_mfma_i32_16x16x64_i8 v[90:93], v[150:153], v[198:201], v[90:93]
	s_setprio 0
	s_setprio 1
	v_mfma_i32_16x16x64_i8 v[134:137], v[154:157], v[170:173], v[134:137]
	v_mfma_i32_16x16x64_i8 v[130:133], v[162:165], v[170:173], v[130:133]
	v_mfma_i32_16x16x64_i8 v[118:121], v[154:157], v[178:181], v[118:121]
	v_mfma_i32_16x16x64_i8 v[114:117], v[162:165], v[178:181], v[114:117]
	v_mfma_i32_16x16x64_i8 v[102:105], v[154:157], v[186:189], v[102:105]
	v_mfma_i32_16x16x64_i8 v[98:101], v[162:165], v[186:189], v[98:101]
	v_mfma_i32_16x16x64_i8 v[86:89], v[154:157], v[194:197], v[86:89]
	v_mfma_i32_16x16x64_i8 v[82:85], v[162:165], v[194:197], v[82:85]
	v_mfma_i32_16x16x64_i8 v[134:137], v[158:161], v[174:177], v[134:137]
	v_mfma_i32_16x16x64_i8 v[130:133], v[166:169], v[174:177], v[130:133]
	v_mfma_i32_16x16x64_i8 v[118:121], v[158:161], v[182:185], v[118:121]
	v_mfma_i32_16x16x64_i8 v[114:117], v[166:169], v[182:185], v[114:117]
	v_mfma_i32_16x16x64_i8 v[102:105], v[158:161], v[190:193], v[102:105]
	v_mfma_i32_16x16x64_i8 v[98:101], v[166:169], v[190:193], v[98:101]
	v_mfma_i32_16x16x64_i8 v[86:89], v[158:161], v[198:201], v[86:89]
	v_mfma_i32_16x16x64_i8 v[82:85], v[166:169], v[198:201], v[82:85]
	s_barrier
	s_setprio 0
	ds_read_b128 v[170:173], v9 offset:49152
	ds_read_b128 v[174:177], v9 offset:50176
	s_or_b32 s61, s60, 0x80
	s_mov_b32 m0, s42
	s_nop 0
	buffer_load_dwordx4 v6, s[8:11], s61 offen lds
	ds_read_b128 v[178:181], v9 offset:51200
	ds_read_b128 v[182:185], v9 offset:52224
	s_add_i32 s60, s60, 0x20080
	s_mov_b32 m0, s43
	s_nop 0
	buffer_load_dwordx4 v7, s[8:11], s61 offen lds
	ds_read_b128 v[186:189], v9 offset:53248
	ds_read_b128 v[190:193], v9 offset:54272
	s_nop 0
	s_mov_b32 m0, s46
	s_nop 0
	buffer_load_dwordx4 v6, s[8:11], s60 offen lds
	ds_read_b128 v[194:197], v9 offset:55296
	ds_read_b128 v[198:201], v9 offset:56320
	s_nop 0
	s_mov_b32 m0, s47
	s_nop 0
	buffer_load_dwordx4 v7, s[8:11], s60 offen lds
	s_nop 0
	s_mov_b32 m0, s44
	s_nop 0
	buffer_load_dwordx4 v6, s[12:15], s59 offen lds
	s_nop 0
	s_mov_b32 m0, s45
	s_nop 0
	buffer_load_dwordx4 v7, s[12:15], s59 offen lds
	s_waitcnt vmcnt(8)
	s_waitcnt lgkmcnt(0)
	s_setprio 1
	s_barrier
	v_mfma_i32_16x16x64_i8 v[78:81], v[26:29], v[170:173], v[78:81]
	v_mfma_i32_16x16x64_i8 v[62:65], v[26:29], v[178:181], v[62:65]
	v_mfma_i32_16x16x64_i8 v[46:49], v[26:29], v[186:189], v[46:49]
	v_mfma_i32_16x16x64_i8 v[10:13], v[26:29], v[194:197], v[10:13]
	v_mfma_i32_16x16x64_i8 v[78:81], v[30:33], v[174:177], v[78:81]
	v_mfma_i32_16x16x64_i8 v[74:77], v[146:149], v[170:173], v[74:77]
	v_mfma_i32_16x16x64_i8 v[62:65], v[30:33], v[182:185], v[62:65]
	v_mfma_i32_16x16x64_i8 v[58:61], v[146:149], v[178:181], v[58:61]
	v_mfma_i32_16x16x64_i8 v[46:49], v[30:33], v[190:193], v[46:49]
	v_mfma_i32_16x16x64_i8 v[42:45], v[146:149], v[186:189], v[42:45]
	v_mfma_i32_16x16x64_i8 v[30:33], v[30:33], v[198:201], v[10:13]
	v_mfma_i32_16x16x64_i8 v[10:13], v[146:149], v[194:197], v[14:17]
	v_mfma_i32_16x16x64_i8 v[74:77], v[150:153], v[174:177], v[74:77]
	v_mfma_i32_16x16x64_i8 v[58:61], v[150:153], v[182:185], v[58:61]
	v_mfma_i32_16x16x64_i8 v[42:45], v[150:153], v[190:193], v[42:45]
	v_mfma_i32_16x16x64_i8 v[26:29], v[150:153], v[198:201], v[10:13]
	s_setprio 0
	s_setprio 1
	v_mfma_i32_16x16x64_i8 v[10:13], v[154:157], v[170:173], v[70:73]
	v_mfma_i32_16x16x64_i8 v[70:73], v[158:161], v[174:177], v[10:13]
	v_mfma_i32_16x16x64_i8 v[10:13], v[162:165], v[170:173], v[66:69]
	v_mfma_i32_16x16x64_i8 v[66:69], v[166:169], v[174:177], v[10:13]
	v_mfma_i32_16x16x64_i8 v[10:13], v[154:157], v[178:181], v[54:57]
	v_mfma_i32_16x16x64_i8 v[54:57], v[158:161], v[182:185], v[10:13]
	v_mfma_i32_16x16x64_i8 v[10:13], v[162:165], v[178:181], v[50:53]
	v_mfma_i32_16x16x64_i8 v[50:53], v[166:169], v[182:185], v[10:13]
	v_mfma_i32_16x16x64_i8 v[10:13], v[154:157], v[186:189], v[38:41]
	v_mfma_i32_16x16x64_i8 v[38:41], v[158:161], v[190:193], v[10:13]
	v_mfma_i32_16x16x64_i8 v[10:13], v[162:165], v[186:189], v[34:37]
	v_mfma_i32_16x16x64_i8 v[34:37], v[166:169], v[190:193], v[10:13]
	v_mfma_i32_16x16x64_i8 v[10:13], v[154:157], v[194:197], v[22:25]
	v_mfma_i32_16x16x64_i8 v[22:25], v[158:161], v[198:201], v[10:13]
	v_mfma_i32_16x16x64_i8 v[10:13], v[162:165], v[194:197], v[18:21]
	v_mfma_i32_16x16x64_i8 v[18:21], v[166:169], v[198:201], v[10:13]
	s_barrier
	s_setprio 0
	s_add_i32 s55, s55, 2
	s_addk_i32 s58, 0x100
	s_cmp_lt_u32 s55, 6
	s_cbranch_scc1 .LBB0_943
	s_andn2_b64 vcc, exec, s[6:7]
	s_cbranch_vccz .LBB0_935
	v_cvt_f32_i32_e32 v142, v142
	v_cvt_f32_i32_e32 v143, v143
	v_cvt_f32_i32_e32 v144, v144
	v_cvt_f32_i32_e32 v145, v145
	v_cvt_f32_i32_e32 v138, v138
	v_cvt_f32_i32_e32 v139, v139
	v_cvt_f32_i32_e32 v140, v140
	v_cvt_f32_i32_e32 v141, v141
	v_cvt_f32_i32_e32 v126, v126
	v_cvt_f32_i32_e32 v127, v127
	v_cvt_f32_i32_e32 v128, v128
	v_cvt_f32_i32_e32 v129, v129
	v_cvt_f32_i32_e32 v122, v122
	v_cvt_f32_i32_e32 v123, v123
	v_cvt_f32_i32_e32 v124, v124
	v_cvt_f32_i32_e32 v125, v125
	v_cvt_f32_i32_e32 v110, v110
	v_cvt_f32_i32_e32 v111, v111
	v_cvt_f32_i32_e32 v112, v112
	v_cvt_f32_i32_e32 v113, v113
	v_cvt_f32_i32_e32 v106, v106
	v_cvt_f32_i32_e32 v107, v107
	v_cvt_f32_i32_e32 v108, v108
	v_cvt_f32_i32_e32 v109, v109
	v_cvt_f32_i32_e32 v94, v94
	v_cvt_f32_i32_e32 v95, v95
	v_cvt_f32_i32_e32 v96, v96
	v_cvt_f32_i32_e32 v97, v97
	v_cvt_f32_i32_e32 v90, v90
	v_cvt_f32_i32_e32 v91, v91
	v_cvt_f32_i32_e32 v92, v92
	v_cvt_f32_i32_e32 v93, v93
	v_cvt_f32_i32_e32 v134, v134
	v_cvt_f32_i32_e32 v135, v135
	v_cvt_f32_i32_e32 v136, v136
	v_cvt_f32_i32_e32 v137, v137
	v_cvt_f32_i32_e32 v130, v130
	v_cvt_f32_i32_e32 v131, v131
	v_cvt_f32_i32_e32 v132, v132
	v_cvt_f32_i32_e32 v133, v133
	v_cvt_f32_i32_e32 v118, v118
	v_cvt_f32_i32_e32 v119, v119
	v_cvt_f32_i32_e32 v120, v120
	v_cvt_f32_i32_e32 v121, v121
	v_cvt_f32_i32_e32 v114, v114
	v_cvt_f32_i32_e32 v115, v115
	v_cvt_f32_i32_e32 v116, v116
	v_cvt_f32_i32_e32 v117, v117
	v_cvt_f32_i32_e32 v102, v102
	v_cvt_f32_i32_e32 v103, v103
	v_cvt_f32_i32_e32 v104, v104
	v_cvt_f32_i32_e32 v105, v105
	v_cvt_f32_i32_e32 v98, v98
	v_cvt_f32_i32_e32 v99, v99
	v_cvt_f32_i32_e32 v100, v100
	v_cvt_f32_i32_e32 v101, v101
	v_cvt_f32_i32_e32 v86, v86
	v_cvt_f32_i32_e32 v87, v87
	v_cvt_f32_i32_e32 v88, v88
	v_cvt_f32_i32_e32 v89, v89
	v_cvt_f32_i32_e32 v82, v82
	v_cvt_f32_i32_e32 v83, v83
	v_cvt_f32_i32_e32 v84, v84
	v_cvt_f32_i32_e32 v85, v85
	v_cvt_f32_i32_e32 v78, v78
	v_cvt_f32_i32_e32 v79, v79
	v_cvt_f32_i32_e32 v80, v80
	v_cvt_f32_i32_e32 v81, v81
	v_cvt_f32_i32_e32 v74, v74
	v_cvt_f32_i32_e32 v75, v75
	v_cvt_f32_i32_e32 v76, v76
	v_cvt_f32_i32_e32 v77, v77
	v_cvt_f32_i32_e32 v62, v62
	v_cvt_f32_i32_e32 v63, v63
	v_cvt_f32_i32_e32 v64, v64
	v_cvt_f32_i32_e32 v65, v65
	v_cvt_f32_i32_e32 v58, v58
	v_cvt_f32_i32_e32 v59, v59
	v_cvt_f32_i32_e32 v60, v60
	v_cvt_f32_i32_e32 v61, v61
	v_cvt_f32_i32_e32 v46, v46
	v_cvt_f32_i32_e32 v47, v47
	v_cvt_f32_i32_e32 v48, v48
	v_cvt_f32_i32_e32 v49, v49
	v_cvt_f32_i32_e32 v42, v42
	v_cvt_f32_i32_e32 v43, v43
	v_cvt_f32_i32_e32 v44, v44
	v_cvt_f32_i32_e32 v45, v45
	v_cvt_f32_i32_e32 v30, v30
	v_cvt_f32_i32_e32 v31, v31
	v_cvt_f32_i32_e32 v32, v32
	v_cvt_f32_i32_e32 v33, v33
	v_cvt_f32_i32_e32 v26, v26
	v_cvt_f32_i32_e32 v27, v27
	v_cvt_f32_i32_e32 v28, v28
	v_cvt_f32_i32_e32 v29, v29
	v_cvt_f32_i32_e32 v70, v70
	v_cvt_f32_i32_e32 v71, v71
	v_cvt_f32_i32_e32 v72, v72
	v_cvt_f32_i32_e32 v73, v73
	v_cvt_f32_i32_e32 v66, v66
	v_cvt_f32_i32_e32 v67, v67
	v_cvt_f32_i32_e32 v68, v68
	v_cvt_f32_i32_e32 v69, v69
	v_cvt_f32_i32_e32 v54, v54
	v_cvt_f32_i32_e32 v55, v55
	v_cvt_f32_i32_e32 v56, v56
	v_cvt_f32_i32_e32 v57, v57
	v_cvt_f32_i32_e32 v50, v50
	v_cvt_f32_i32_e32 v51, v51
	v_cvt_f32_i32_e32 v52, v52
	v_cvt_f32_i32_e32 v53, v53
	v_cvt_f32_i32_e32 v38, v38
	v_cvt_f32_i32_e32 v39, v39
	v_cvt_f32_i32_e32 v40, v40
	v_cvt_f32_i32_e32 v41, v41
	v_cvt_f32_i32_e32 v34, v34
	v_cvt_f32_i32_e32 v35, v35
	v_cvt_f32_i32_e32 v36, v36
	v_cvt_f32_i32_e32 v37, v37
	v_cvt_f32_i32_e32 v22, v22
	v_cvt_f32_i32_e32 v23, v23
	v_cvt_f32_i32_e32 v24, v24
	v_cvt_f32_i32_e32 v25, v25
	v_cvt_f32_i32_e32 v18, v18
	v_cvt_f32_i32_e32 v19, v19
	v_cvt_f32_i32_e32 v20, v20
	v_cvt_f32_i32_e32 v21, v21
	s_andn2_b64 vcc, exec, s[4:5]
	s_cbranch_vccnz .LBB0_936

.LBB0_1072:
	ds_read_b128 v[136:139], v152
	ds_read_b128 v[140:143], v152 offset:1024
	ds_read_b128 v[158:161], v152 offset:2048
	ds_read_b128 v[162:165], v152 offset:3072
	ds_read_b128 v[166:169], v153
	ds_read_b128 v[170:173], v153 offset:1024
	ds_read_b128 v[174:177], v153 offset:2048
	ds_read_b128 v[178:181], v153 offset:3072
	s_add_i32 s60, s55, 0xfffe0080
	s_cmp_eq_u32 s59, 4
	s_cselect_b32 s62, s1, s60
	s_cselect_b32 s61, s54, s58
	s_or_b32 s60, s62, 0x80
	s_mov_b32 m0, s42
	s_nop 0
	buffer_load_dwordx4 v146, s[12:15], s55 offen lds
	s_nop 0
	s_mov_b32 m0, s43
	s_nop 0
	buffer_load_dwordx4 v147, s[12:15], s55 offen lds
	ds_read_b128 v[182:185], v154
	ds_read_b128 v[186:189], v154 offset:1024
	ds_read_b128 v[190:193], v154 offset:2048
	ds_read_b128 v[194:197], v154 offset:3072
	ds_read_b128 v[198:201], v154 offset:4096
	ds_read_b128 v[202:205], v154 offset:5120
	ds_read_b128 v[206:209], v154 offset:6144
	ds_read_b128 v[210:213], v154 offset:7168
	s_waitcnt vmcnt(8)
	s_waitcnt lgkmcnt(0)
	s_setprio 1
	s_barrier
	v_mfma_i32_16x16x64_i8 v[126:129], v[136:139], v[182:185], v[126:129]
	v_mfma_i32_16x16x64_i8 v[122:125], v[158:161], v[182:185], v[122:125]
	v_mfma_i32_16x16x64_i8 v[118:121], v[136:139], v[190:193], v[118:121]
	v_mfma_i32_16x16x64_i8 v[114:117], v[158:161], v[190:193], v[114:117]
	v_mfma_i32_16x16x64_i8 v[110:113], v[136:139], v[198:201], v[110:113]
	v_mfma_i32_16x16x64_i8 v[106:109], v[158:161], v[198:201], v[106:109]
	v_mfma_i32_16x16x64_i8 v[102:105], v[136:139], v[206:209], v[102:105]
	v_mfma_i32_16x16x64_i8 v[98:101], v[158:161], v[206:209], v[98:101]
	v_mfma_i32_16x16x64_i8 v[126:129], v[140:143], v[186:189], v[126:129]
	v_mfma_i32_16x16x64_i8 v[122:125], v[162:165], v[186:189], v[122:125]
	v_mfma_i32_16x16x64_i8 v[118:121], v[140:143], v[194:197], v[118:121]
	v_mfma_i32_16x16x64_i8 v[114:117], v[162:165], v[194:197], v[114:117]
	v_mfma_i32_16x16x64_i8 v[110:113], v[140:143], v[202:205], v[110:113]
	v_mfma_i32_16x16x64_i8 v[106:109], v[162:165], v[202:205], v[106:109]
	v_mfma_i32_16x16x64_i8 v[102:105], v[140:143], v[210:213], v[102:105]
	v_mfma_i32_16x16x64_i8 v[98:101], v[162:165], v[210:213], v[98:101]
	s_setprio 0
	s_setprio 1
	v_mfma_i32_16x16x64_i8 v[94:97], v[166:169], v[182:185], v[94:97]
	v_mfma_i32_16x16x64_i8 v[90:93], v[174:177], v[182:185], v[90:93]
	v_mfma_i32_16x16x64_i8 v[86:89], v[166:169], v[190:193], v[86:89]
	v_mfma_i32_16x16x64_i8 v[82:85], v[174:177], v[190:193], v[82:85]
	v_mfma_i32_16x16x64_i8 v[78:81], v[166:169], v[198:201], v[78:81]
	v_mfma_i32_16x16x64_i8 v[74:77], v[174:177], v[198:201], v[74:77]
	v_mfma_i32_16x16x64_i8 v[70:73], v[166:169], v[206:209], v[70:73]
	v_mfma_i32_16x16x64_i8 v[66:69], v[174:177], v[206:209], v[66:69]
	v_mfma_i32_16x16x64_i8 v[94:97], v[170:173], v[186:189], v[94:97]
	v_mfma_i32_16x16x64_i8 v[90:93], v[178:181], v[186:189], v[90:93]
	v_mfma_i32_16x16x64_i8 v[86:89], v[170:173], v[194:197], v[86:89]
	v_mfma_i32_16x16x64_i8 v[82:85], v[178:181], v[194:197], v[82:85]
	v_mfma_i32_16x16x64_i8 v[78:81], v[170:173], v[202:205], v[78:81]
	v_mfma_i32_16x16x64_i8 v[74:77], v[178:181], v[202:205], v[74:77]
	v_mfma_i32_16x16x64_i8 v[70:73], v[170:173], v[210:213], v[70:73]
	v_mfma_i32_16x16x64_i8 v[66:69], v[178:181], v[210:213], v[66:69]
	s_barrier
	s_setprio 0
	ds_read_b128 v[182:185], v154 offset:16384
	ds_read_b128 v[186:189], v154 offset:17408
	s_mov_b32 m0, s27
	s_nop 0
	buffer_load_dwordx4 v144, s[8:11], s61 offen lds
	ds_read_b128 v[190:193], v154 offset:18432
	ds_read_b128 v[194:197], v154 offset:19456
	s_add_i32 s63, s61, 0x20000
	s_mov_b32 m0, s28
	s_nop 0
	buffer_load_dwordx4 v145, s[8:11], s61 offen lds
	ds_read_b128 v[198:201], v154 offset:20480
	ds_read_b128 v[202:205], v154 offset:21504
	s_nop 0
	s_mov_b32 m0, s29
	s_nop 0
	buffer_load_dwordx4 v144, s[8:11], s63 offen lds
	ds_read_b128 v[206:209], v154 offset:22528
	ds_read_b128 v[210:213], v154 offset:23552
	s_nop 0
	s_mov_b32 m0, s30
	s_nop 0
	buffer_load_dwordx4 v145, s[8:11], s63 offen lds
	s_nop 0
	s_mov_b32 m0, s26
	s_nop 0
	buffer_load_dwordx4 v146, s[12:15], s62 offen lds
	s_nop 0
	s_mov_b32 m0, s2
	s_nop 0
	buffer_load_dwordx4 v147, s[12:15], s62 offen lds
	s_waitcnt vmcnt(8)
	s_waitcnt lgkmcnt(0)
	s_setprio 1
	s_barrier
	v_mfma_i32_16x16x64_i8 v[62:65], v[136:139], v[182:185], v[62:65]
	v_mfma_i32_16x16x64_i8 v[58:61], v[158:161], v[182:185], v[58:61]
	v_mfma_i32_16x16x64_i8 v[54:57], v[136:139], v[190:193], v[54:57]
	v_mfma_i32_16x16x64_i8 v[50:53], v[158:161], v[190:193], v[50:53]
	v_mfma_i32_16x16x64_i8 v[46:49], v[136:139], v[198:201], v[46:49]
	v_mfma_i32_16x16x64_i8 v[42:45], v[158:161], v[198:201], v[42:45]
	v_mfma_i32_16x16x64_i8 v[38:41], v[136:139], v[206:209], v[38:41]
	v_mfma_i32_16x16x64_i8 v[34:37], v[158:161], v[206:209], v[34:37]
	v_mfma_i32_16x16x64_i8 v[62:65], v[140:143], v[186:189], v[62:65]
	v_mfma_i32_16x16x64_i8 v[58:61], v[162:165], v[186:189], v[58:61]
	v_mfma_i32_16x16x64_i8 v[54:57], v[140:143], v[194:197], v[54:57]
	v_mfma_i32_16x16x64_i8 v[50:53], v[162:165], v[194:197], v[50:53]
	v_mfma_i32_16x16x64_i8 v[46:49], v[140:143], v[202:205], v[46:49]
	v_mfma_i32_16x16x64_i8 v[42:45], v[162:165], v[202:205], v[42:45]
	v_mfma_i32_16x16x64_i8 v[38:41], v[140:143], v[210:213], v[38:41]
	v_mfma_i32_16x16x64_i8 v[34:37], v[162:165], v[210:213], v[34:37]
	s_setprio 0
	s_setprio 1
	v_mfma_i32_16x16x64_i8 v[30:33], v[166:169], v[182:185], v[30:33]
	v_mfma_i32_16x16x64_i8 v[26:29], v[174:177], v[182:185], v[26:29]
	v_mfma_i32_16x16x64_i8 v[22:25], v[166:169], v[190:193], v[22:25]
	v_mfma_i32_16x16x64_i8 v[18:21], v[174:177], v[190:193], v[18:21]
	v_mfma_i32_16x16x64_i8 v[14:17], v[166:169], v[198:201], v[14:17]
	v_mfma_i32_16x16x64_i8 v[10:13], v[174:177], v[198:201], v[10:13]
	v_mfma_i32_16x16x64_i8 v[6:9], v[166:169], v[206:209], v[6:9]
	v_mfma_i32_16x16x64_i8 v[2:5], v[174:177], v[206:209], v[2:5]
	v_mfma_i32_16x16x64_i8 v[30:33], v[170:173], v[186:189], v[30:33]
	v_mfma_i32_16x16x64_i8 v[26:29], v[178:181], v[186:189], v[26:29]
	v_mfma_i32_16x16x64_i8 v[22:25], v[170:173], v[194:197], v[22:25]
	v_mfma_i32_16x16x64_i8 v[18:21], v[178:181], v[194:197], v[18:21]
	v_mfma_i32_16x16x64_i8 v[14:17], v[170:173], v[202:205], v[14:17]
	v_mfma_i32_16x16x64_i8 v[10:13], v[178:181], v[202:205], v[10:13]
	v_mfma_i32_16x16x64_i8 v[6:9], v[170:173], v[210:213], v[6:9]
	v_mfma_i32_16x16x64_i8 v[2:5], v[178:181], v[210:213], v[2:5]
	s_barrier
	s_setprio 0
	ds_read_b128 v[136:139], v155
	ds_read_b128 v[140:143], v155 offset:1024
	ds_read_b128 v[158:161], v155 offset:2048
	ds_read_b128 v[162:165], v155 offset:3072
	ds_read_b128 v[166:169], v156
	ds_read_b128 v[170:173], v156 offset:1024
	ds_read_b128 v[174:177], v156 offset:2048
	ds_read_b128 v[178:181], v156 offset:3072
	s_add_i32 s62, s62, 0x20000
	s_mov_b32 m0, s3
	s_nop 0
	buffer_load_dwordx4 v146, s[12:15], s62 offen lds
	s_nop 0
	s_mov_b32 m0, s31
	s_nop 0
	buffer_load_dwordx4 v147, s[12:15], s62 offen lds
	ds_read_b128 v[182:185], v154 offset:32768
	ds_read_b128 v[186:189], v154 offset:33792
	ds_read_b128 v[190:193], v154 offset:34816
	ds_read_b128 v[194:197], v154 offset:35840
	ds_read_b128 v[198:201], v154 offset:36864
	ds_read_b128 v[202:205], v154 offset:37888
	ds_read_b128 v[206:209], v154 offset:38912
	ds_read_b128 v[210:213], v154 offset:39936
	s_waitcnt vmcnt(8)
	s_waitcnt lgkmcnt(0)
	s_setprio 1
	s_barrier
	v_mfma_i32_16x16x64_i8 v[126:129], v[136:139], v[182:185], v[126:129]
	v_mfma_i32_16x16x64_i8 v[122:125], v[158:161], v[182:185], v[122:125]
	v_mfma_i32_16x16x64_i8 v[118:121], v[136:139], v[190:193], v[118:121]
	v_mfma_i32_16x16x64_i8 v[114:117], v[158:161], v[190:193], v[114:117]
	v_mfma_i32_16x16x64_i8 v[110:113], v[136:139], v[198:201], v[110:113]
	v_mfma_i32_16x16x64_i8 v[106:109], v[158:161], v[198:201], v[106:109]
	v_mfma_i32_16x16x64_i8 v[102:105], v[136:139], v[206:209], v[102:105]
	v_mfma_i32_16x16x64_i8 v[98:101], v[158:161], v[206:209], v[98:101]
	v_mfma_i32_16x16x64_i8 v[126:129], v[140:143], v[186:189], v[126:129]
	v_mfma_i32_16x16x64_i8 v[122:125], v[162:165], v[186:189], v[122:125]
	v_mfma_i32_16x16x64_i8 v[118:121], v[140:143], v[194:197], v[118:121]
	v_mfma_i32_16x16x64_i8 v[114:117], v[162:165], v[194:197], v[114:117]
	v_mfma_i32_16x16x64_i8 v[110:113], v[140:143], v[202:205], v[110:113]
	v_mfma_i32_16x16x64_i8 v[106:109], v[162:165], v[202:205], v[106:109]
	v_mfma_i32_16x16x64_i8 v[102:105], v[140:143], v[210:213], v[102:105]
	v_mfma_i32_16x16x64_i8 v[98:101], v[162:165], v[210:213], v[98:101]
	s_setprio 0
	s_setprio 1
	v_mfma_i32_16x16x64_i8 v[94:97], v[166:169], v[182:185], v[94:97]
	v_mfma_i32_16x16x64_i8 v[90:93], v[174:177], v[182:185], v[90:93]
	v_mfma_i32_16x16x64_i8 v[86:89], v[166:169], v[190:193], v[86:89]
	v_mfma_i32_16x16x64_i8 v[82:85], v[174:177], v[190:193], v[82:85]
	v_mfma_i32_16x16x64_i8 v[78:81], v[166:169], v[198:201], v[78:81]
	v_mfma_i32_16x16x64_i8 v[74:77], v[174:177], v[198:201], v[74:77]
	v_mfma_i32_16x16x64_i8 v[70:73], v[166:169], v[206:209], v[70:73]
	v_mfma_i32_16x16x64_i8 v[66:69], v[174:177], v[206:209], v[66:69]
	v_mfma_i32_16x16x64_i8 v[94:97], v[170:173], v[186:189], v[94:97]
	v_mfma_i32_16x16x64_i8 v[90:93], v[178:181], v[186:189], v[90:93]
	v_mfma_i32_16x16x64_i8 v[86:89], v[170:173], v[194:197], v[86:89]
	v_mfma_i32_16x16x64_i8 v[82:85], v[178:181], v[194:197], v[82:85]
	v_mfma_i32_16x16x64_i8 v[78:81], v[170:173], v[202:205], v[78:81]
	v_mfma_i32_16x16x64_i8 v[74:77], v[178:181], v[202:205], v[74:77]
	v_mfma_i32_16x16x64_i8 v[70:73], v[170:173], v[210:213], v[70:73]
	v_mfma_i32_16x16x64_i8 v[66:69], v[178:181], v[210:213], v[66:69]
	s_barrier
	s_setprio 0
	ds_read_b128 v[182:185], v154 offset:49152
	ds_read_b128 v[186:189], v154 offset:50176
	s_or_b32 s62, s61, 0x80
	s_mov_b32 m0, s35
	s_nop 0
	buffer_load_dwordx4 v144, s[8:11], s62 offen lds
	ds_read_b128 v[190:193], v154 offset:51200
	ds_read_b128 v[194:197], v154 offset:52224
	s_add_i32 s61, s61, 0x20080
	s_mov_b32 m0, s36
	s_nop 0
	buffer_load_dwordx4 v145, s[8:11], s62 offen lds
	ds_read_b128 v[198:201], v154 offset:53248
	ds_read_b128 v[202:205], v154 offset:54272
	s_nop 0
	s_mov_b32 m0, s39
	s_nop 0
	buffer_load_dwordx4 v144, s[8:11], s61 offen lds
	ds_read_b128 v[206:209], v154 offset:55296
	ds_read_b128 v[210:213], v154 offset:56320
	s_nop 0
	s_mov_b32 m0, s40
	s_nop 0
	buffer_load_dwordx4 v145, s[8:11], s61 offen lds
	s_nop 0
	s_mov_b32 m0, s37
	s_nop 0
	buffer_load_dwordx4 v146, s[12:15], s60 offen lds
	s_nop 0
	s_mov_b32 m0, s38
	s_nop 0
	buffer_load_dwordx4 v147, s[12:15], s60 offen lds
	s_waitcnt vmcnt(8)
	s_waitcnt lgkmcnt(0)
	s_setprio 1
	s_barrier
	v_mfma_i32_16x16x64_i8 v[62:65], v[136:139], v[182:185], v[62:65]
	v_mfma_i32_16x16x64_i8 v[58:61], v[158:161], v[182:185], v[58:61]
	v_mfma_i32_16x16x64_i8 v[54:57], v[136:139], v[190:193], v[54:57]
	v_mfma_i32_16x16x64_i8 v[50:53], v[158:161], v[190:193], v[50:53]
	v_mfma_i32_16x16x64_i8 v[46:49], v[136:139], v[198:201], v[46:49]
	v_mfma_i32_16x16x64_i8 v[42:45], v[158:161], v[198:201], v[42:45]
	v_mfma_i32_16x16x64_i8 v[38:41], v[136:139], v[206:209], v[38:41]
	v_mfma_i32_16x16x64_i8 v[34:37], v[158:161], v[206:209], v[34:37]
	v_mfma_i32_16x16x64_i8 v[62:65], v[140:143], v[186:189], v[62:65]
	v_mfma_i32_16x16x64_i8 v[58:61], v[162:165], v[186:189], v[58:61]
	v_mfma_i32_16x16x64_i8 v[54:57], v[140:143], v[194:197], v[54:57]
	v_mfma_i32_16x16x64_i8 v[50:53], v[162:165], v[194:197], v[50:53]
	v_mfma_i32_16x16x64_i8 v[46:49], v[140:143], v[202:205], v[46:49]
	v_mfma_i32_16x16x64_i8 v[42:45], v[162:165], v[202:205], v[42:45]
	v_mfma_i32_16x16x64_i8 v[38:41], v[140:143], v[210:213], v[38:41]
	v_mfma_i32_16x16x64_i8 v[34:37], v[162:165], v[210:213], v[34:37]
	s_setprio 0
	s_setprio 1
	v_mfma_i32_16x16x64_i8 v[30:33], v[166:169], v[182:185], v[30:33]
	v_mfma_i32_16x16x64_i8 v[26:29], v[174:177], v[182:185], v[26:29]
	v_mfma_i32_16x16x64_i8 v[22:25], v[166:169], v[190:193], v[22:25]
	v_mfma_i32_16x16x64_i8 v[18:21], v[174:177], v[190:193], v[18:21]
	v_mfma_i32_16x16x64_i8 v[14:17], v[166:169], v[198:201], v[14:17]
	v_mfma_i32_16x16x64_i8 v[10:13], v[174:177], v[198:201], v[10:13]
	v_mfma_i32_16x16x64_i8 v[6:9], v[166:169], v[206:209], v[6:9]
	v_mfma_i32_16x16x64_i8 v[2:5], v[174:177], v[206:209], v[2:5]
	v_mfma_i32_16x16x64_i8 v[30:33], v[170:173], v[186:189], v[30:33]
	v_mfma_i32_16x16x64_i8 v[26:29], v[178:181], v[186:189], v[26:29]
	v_mfma_i32_16x16x64_i8 v[22:25], v[170:173], v[194:197], v[22:25]
	v_mfma_i32_16x16x64_i8 v[18:21], v[178:181], v[194:197], v[18:21]
	v_mfma_i32_16x16x64_i8 v[14:17], v[170:173], v[202:205], v[14:17]
	v_mfma_i32_16x16x64_i8 v[10:13], v[178:181], v[202:205], v[10:13]
	v_mfma_i32_16x16x64_i8 v[6:9], v[170:173], v[210:213], v[6:9]
	v_mfma_i32_16x16x64_i8 v[2:5], v[178:181], v[210:213], v[2:5]
	s_barrier
	s_setprio 0
	s_add_i32 s59, s59, 2
	s_addk_i32 s55, 0x100
	s_addk_i32 s58, 0x100
	s_cmp_gt_u32 s59, 5
	s_cbranch_scc0 .LBB0_1072
	s_and_b64 vcc, exec, s[20:21]
	s_cbranch_vccz .LBB0_1075
	s_barrier

.LBB0_1135:
	v_add_u32_e32 v150, 0x10000, v136
	v_add_u32_e32 v166, 0x14000, v136
	ds_read_b128 v[138:141], v150
	ds_read_b128 v[142:145], v150 offset:1024
	ds_read_b128 v[146:149], v150 offset:2048
	ds_read_b128 v[150:153], v150 offset:3072
	ds_read_b128 v[154:157], v166
	ds_read_b128 v[158:161], v166 offset:1024
	ds_read_b128 v[162:165], v166 offset:2048
	ds_read_b128 v[166:169], v166 offset:3072
	s_add_i32 s57, s36, s3
	s_add_i32 s56, s30, s3
	s_add_i32 s55, s57, 0x1600
	s_addk_i32 s56, 0x1600
	s_cmp_eq_u32 s3, 0
	s_cselect_b32 s58, s53, s55
	s_cselect_b32 s56, s54, s56
	s_add_i32 s55, s58, 0x80
	s_add_i32 s57, s57, 0xb1580
	s_mov_b32 m0, s46
	s_nop 0
	buffer_load_dwordx4 v134, s[16:19], s57 offen lds
	s_nop 0
	s_mov_b32 m0, s47
	s_nop 0
	buffer_load_dwordx4 v135, s[16:19], s57 offen lds
	ds_read_b128 v[170:173], v137
	ds_read_b128 v[174:177], v137 offset:1024
	ds_read_b128 v[178:181], v137 offset:2048
	ds_read_b128 v[182:185], v137 offset:3072
	ds_read_b128 v[186:189], v137 offset:4096
	ds_read_b128 v[190:193], v137 offset:5120
	ds_read_b128 v[194:197], v137 offset:6144
	ds_read_b128 v[198:201], v137 offset:7168
	s_waitcnt vmcnt(8)
	s_waitcnt lgkmcnt(0)
	s_setprio 1
	s_barrier
	v_mfma_f32_16x16x32_bf16 v[126:129], v[138:141], v[170:173], v[126:129]
	v_mfma_f32_16x16x32_bf16 v[122:125], v[146:149], v[170:173], v[122:125]
	v_mfma_f32_16x16x32_bf16 v[118:121], v[138:141], v[178:181], v[118:121]
	v_mfma_f32_16x16x32_bf16 v[106:109], v[146:149], v[178:181], v[106:109]
	v_mfma_f32_16x16x32_bf16 v[102:105], v[138:141], v[186:189], v[102:105]
	v_mfma_f32_16x16x32_bf16 v[90:93], v[146:149], v[186:189], v[90:93]
	v_mfma_f32_16x16x32_bf16 v[86:89], v[138:141], v[194:197], v[86:89]
	v_mfma_f32_16x16x32_bf16 v[74:77], v[146:149], v[194:197], v[74:77]
	v_mfma_f32_16x16x32_bf16 v[126:129], v[142:145], v[174:177], v[126:129]
	v_mfma_f32_16x16x32_bf16 v[122:125], v[150:153], v[174:177], v[122:125]
	v_mfma_f32_16x16x32_bf16 v[118:121], v[142:145], v[182:185], v[118:121]
	v_mfma_f32_16x16x32_bf16 v[106:109], v[150:153], v[182:185], v[106:109]
	v_mfma_f32_16x16x32_bf16 v[102:105], v[142:145], v[190:193], v[102:105]
	v_mfma_f32_16x16x32_bf16 v[90:93], v[150:153], v[190:193], v[90:93]
	v_mfma_f32_16x16x32_bf16 v[86:89], v[142:145], v[198:201], v[86:89]
	v_mfma_f32_16x16x32_bf16 v[74:77], v[150:153], v[198:201], v[74:77]
	s_setprio 0
	s_setprio 1
	v_mfma_f32_16x16x32_bf16 v[114:117], v[154:157], v[170:173], v[114:117]
	v_mfma_f32_16x16x32_bf16 v[110:113], v[162:165], v[170:173], v[110:113]
	v_mfma_f32_16x16x32_bf16 v[98:101], v[154:157], v[178:181], v[98:101]
	v_mfma_f32_16x16x32_bf16 v[94:97], v[162:165], v[178:181], v[94:97]
	v_mfma_f32_16x16x32_bf16 v[82:85], v[154:157], v[186:189], v[82:85]
	v_mfma_f32_16x16x32_bf16 v[78:81], v[162:165], v[186:189], v[78:81]
	v_mfma_f32_16x16x32_bf16 v[70:73], v[154:157], v[194:197], v[70:73]
	v_mfma_f32_16x16x32_bf16 v[66:69], v[162:165], v[194:197], v[66:69]
	v_mfma_f32_16x16x32_bf16 v[114:117], v[158:161], v[174:177], v[114:117]
	v_mfma_f32_16x16x32_bf16 v[110:113], v[166:169], v[174:177], v[110:113]
	v_mfma_f32_16x16x32_bf16 v[98:101], v[158:161], v[182:185], v[98:101]
	v_mfma_f32_16x16x32_bf16 v[94:97], v[166:169], v[182:185], v[94:97]
	v_mfma_f32_16x16x32_bf16 v[82:85], v[158:161], v[190:193], v[82:85]
	v_mfma_f32_16x16x32_bf16 v[78:81], v[166:169], v[190:193], v[78:81]
	v_mfma_f32_16x16x32_bf16 v[70:73], v[158:161], v[198:201], v[70:73]
	v_mfma_f32_16x16x32_bf16 v[66:69], v[166:169], v[198:201], v[66:69]
	s_barrier
	s_setprio 0
	ds_read_b128 v[170:173], v137 offset:16384
	ds_read_b128 v[174:177], v137 offset:17408
	s_mov_b32 m0, s29
	s_nop 0
	buffer_load_dwordx4 v134, s[12:15], s56 offen lds
	ds_read_b128 v[178:181], v137 offset:18432
	ds_read_b128 v[182:185], v137 offset:19456
	s_add_i32 s57, s56, 0xb0000
	s_mov_b32 m0, s33
	s_nop 0
	buffer_load_dwordx4 v135, s[12:15], s56 offen lds
	ds_read_b128 v[186:189], v137 offset:20480
	ds_read_b128 v[190:193], v137 offset:21504
	s_nop 0
	s_mov_b32 m0, s34
	s_nop 0
	buffer_load_dwordx4 v134, s[12:15], s57 offen lds
	ds_read_b128 v[194:197], v137 offset:22528
	ds_read_b128 v[198:201], v137 offset:23552
	s_nop 0
	s_mov_b32 m0, s35
	s_nop 0
	buffer_load_dwordx4 v135, s[12:15], s57 offen lds
	s_nop 0
	s_mov_b32 m0, s28
	s_nop 0
	buffer_load_dwordx4 v134, s[16:19], s58 offen lds
	s_nop 0
	s_mov_b32 m0, s37
	s_nop 0
	buffer_load_dwordx4 v135, s[16:19], s58 offen lds
	s_waitcnt vmcnt(8)
	s_waitcnt lgkmcnt(0)
	s_setprio 1
	s_barrier
	v_mfma_f32_16x16x32_bf16 v[62:65], v[138:141], v[170:173], v[62:65]
	v_mfma_f32_16x16x32_bf16 v[58:61], v[146:149], v[170:173], v[58:61]
	v_mfma_f32_16x16x32_bf16 v[54:57], v[138:141], v[178:181], v[54:57]
	v_mfma_f32_16x16x32_bf16 v[42:45], v[146:149], v[178:181], v[42:45]
	v_mfma_f32_16x16x32_bf16 v[38:41], v[138:141], v[186:189], v[38:41]
	v_mfma_f32_16x16x32_bf16 v[26:29], v[146:149], v[186:189], v[26:29]
	v_mfma_f32_16x16x32_bf16 v[18:21], v[138:141], v[194:197], v[18:21]
	v_mfma_f32_16x16x32_bf16 v[10:13], v[146:149], v[194:197], v[10:13]
	v_mfma_f32_16x16x32_bf16 v[62:65], v[142:145], v[174:177], v[62:65]
	v_mfma_f32_16x16x32_bf16 v[58:61], v[150:153], v[174:177], v[58:61]
	v_mfma_f32_16x16x32_bf16 v[54:57], v[142:145], v[182:185], v[54:57]
	v_mfma_f32_16x16x32_bf16 v[42:45], v[150:153], v[182:185], v[42:45]
	v_mfma_f32_16x16x32_bf16 v[38:41], v[142:145], v[190:193], v[38:41]
	v_mfma_f32_16x16x32_bf16 v[26:29], v[150:153], v[190:193], v[26:29]
	v_mfma_f32_16x16x32_bf16 v[18:21], v[142:145], v[198:201], v[18:21]
	v_mfma_f32_16x16x32_bf16 v[10:13], v[150:153], v[198:201], v[10:13]
	s_setprio 0
	s_setprio 1
	v_mfma_f32_16x16x32_bf16 v[50:53], v[154:157], v[170:173], v[50:53]
	v_mfma_f32_16x16x32_bf16 v[46:49], v[162:165], v[170:173], v[46:49]
	v_mfma_f32_16x16x32_bf16 v[34:37], v[154:157], v[178:181], v[34:37]
	v_mfma_f32_16x16x32_bf16 v[30:33], v[162:165], v[178:181], v[30:33]
	v_mfma_f32_16x16x32_bf16 v[22:25], v[154:157], v[186:189], v[22:25]
	v_mfma_f32_16x16x32_bf16 v[14:17], v[162:165], v[186:189], v[14:17]
	v_mfma_f32_16x16x32_bf16 v[6:9], v[154:157], v[194:197], v[6:9]
	v_mfma_f32_16x16x32_bf16 v[2:5], v[162:165], v[194:197], v[2:5]
	v_mfma_f32_16x16x32_bf16 v[50:53], v[158:161], v[174:177], v[50:53]
	v_mfma_f32_16x16x32_bf16 v[46:49], v[166:169], v[174:177], v[46:49]
	v_mfma_f32_16x16x32_bf16 v[34:37], v[158:161], v[182:185], v[34:37]
	v_mfma_f32_16x16x32_bf16 v[30:33], v[166:169], v[182:185], v[30:33]
	v_mfma_f32_16x16x32_bf16 v[22:25], v[158:161], v[190:193], v[22:25]
	v_mfma_f32_16x16x32_bf16 v[14:17], v[166:169], v[190:193], v[14:17]
	v_mfma_f32_16x16x32_bf16 v[6:9], v[158:161], v[198:201], v[6:9]
	v_mfma_f32_16x16x32_bf16 v[2:5], v[166:169], v[198:201], v[2:5]
	s_barrier
	s_setprio 0
	v_add_u32_e32 v150, 0x18000, v136
	v_add_u32_e32 v166, 0x1c000, v136
	ds_read_b128 v[138:141], v150
	ds_read_b128 v[142:145], v150 offset:1024
	ds_read_b128 v[146:149], v150 offset:2048
	ds_read_b128 v[150:153], v150 offset:3072
	ds_read_b128 v[154:157], v166
	ds_read_b128 v[158:161], v166 offset:1024
	ds_read_b128 v[162:165], v166 offset:2048
	ds_read_b128 v[166:169], v166 offset:3072
	s_add_i32 s57, s58, 0xb0000
	s_mov_b32 m0, s38
	s_nop 0
	buffer_load_dwordx4 v134, s[16:19], s57 offen lds
	s_nop 0
	s_mov_b32 m0, s39
	s_nop 0
	buffer_load_dwordx4 v135, s[16:19], s57 offen lds
	ds_read_b128 v[170:173], v137 offset:32768
	ds_read_b128 v[174:177], v137 offset:33792
	ds_read_b128 v[178:181], v137 offset:34816
	ds_read_b128 v[182:185], v137 offset:35840
	ds_read_b128 v[186:189], v137 offset:36864
	ds_read_b128 v[190:193], v137 offset:37888
	ds_read_b128 v[194:197], v137 offset:38912
	ds_read_b128 v[198:201], v137 offset:39936
	s_waitcnt vmcnt(8)
	s_waitcnt lgkmcnt(0)
	s_setprio 1
	s_barrier
	v_mfma_f32_16x16x32_bf16 v[126:129], v[138:141], v[170:173], v[126:129]
	v_mfma_f32_16x16x32_bf16 v[122:125], v[146:149], v[170:173], v[122:125]
	v_mfma_f32_16x16x32_bf16 v[118:121], v[138:141], v[178:181], v[118:121]
	v_mfma_f32_16x16x32_bf16 v[106:109], v[146:149], v[178:181], v[106:109]
	v_mfma_f32_16x16x32_bf16 v[102:105], v[138:141], v[186:189], v[102:105]
	v_mfma_f32_16x16x32_bf16 v[90:93], v[146:149], v[186:189], v[90:93]
	v_mfma_f32_16x16x32_bf16 v[86:89], v[138:141], v[194:197], v[86:89]
	v_mfma_f32_16x16x32_bf16 v[74:77], v[146:149], v[194:197], v[74:77]
	v_mfma_f32_16x16x32_bf16 v[126:129], v[142:145], v[174:177], v[126:129]
	v_mfma_f32_16x16x32_bf16 v[122:125], v[150:153], v[174:177], v[122:125]
	v_mfma_f32_16x16x32_bf16 v[118:121], v[142:145], v[182:185], v[118:121]
	v_mfma_f32_16x16x32_bf16 v[106:109], v[150:153], v[182:185], v[106:109]
	v_mfma_f32_16x16x32_bf16 v[102:105], v[142:145], v[190:193], v[102:105]
	v_mfma_f32_16x16x32_bf16 v[90:93], v[150:153], v[190:193], v[90:93]
	v_mfma_f32_16x16x32_bf16 v[86:89], v[142:145], v[198:201], v[86:89]
	v_mfma_f32_16x16x32_bf16 v[74:77], v[150:153], v[198:201], v[74:77]
	s_setprio 0
	s_setprio 1
	v_mfma_f32_16x16x32_bf16 v[114:117], v[154:157], v[170:173], v[114:117]
	v_mfma_f32_16x16x32_bf16 v[110:113], v[162:165], v[170:173], v[110:113]
	v_mfma_f32_16x16x32_bf16 v[98:101], v[154:157], v[178:181], v[98:101]
	v_mfma_f32_16x16x32_bf16 v[94:97], v[162:165], v[178:181], v[94:97]
	v_mfma_f32_16x16x32_bf16 v[82:85], v[154:157], v[186:189], v[82:85]
	v_mfma_f32_16x16x32_bf16 v[78:81], v[162:165], v[186:189], v[78:81]
	v_mfma_f32_16x16x32_bf16 v[70:73], v[154:157], v[194:197], v[70:73]
	v_mfma_f32_16x16x32_bf16 v[66:69], v[162:165], v[194:197], v[66:69]
	v_mfma_f32_16x16x32_bf16 v[114:117], v[158:161], v[174:177], v[114:117]
	v_mfma_f32_16x16x32_bf16 v[110:113], v[166:169], v[174:177], v[110:113]
	v_mfma_f32_16x16x32_bf16 v[98:101], v[158:161], v[182:185], v[98:101]
	v_mfma_f32_16x16x32_bf16 v[94:97], v[166:169], v[182:185], v[94:97]
	v_mfma_f32_16x16x32_bf16 v[82:85], v[158:161], v[190:193], v[82:85]
	v_mfma_f32_16x16x32_bf16 v[78:81], v[166:169], v[190:193], v[78:81]
	v_mfma_f32_16x16x32_bf16 v[70:73], v[158:161], v[198:201], v[70:73]
	v_mfma_f32_16x16x32_bf16 v[66:69], v[166:169], v[198:201], v[66:69]
	s_barrier
	s_setprio 0
	ds_read_b128 v[170:173], v137 offset:49152
	ds_read_b128 v[174:177], v137 offset:50176
	s_add_i32 s57, s56, 0x80
	s_mov_b32 m0, s40
	s_nop 0
	buffer_load_dwordx4 v134, s[12:15], s57 offen lds
	ds_read_b128 v[178:181], v137 offset:51200
	ds_read_b128 v[182:185], v137 offset:52224
	s_add_i32 s56, s56, 0xb0080
	s_mov_b32 m0, s41
	s_nop 0
	buffer_load_dwordx4 v135, s[12:15], s57 offen lds
	ds_read_b128 v[186:189], v137 offset:53248
	ds_read_b128 v[190:193], v137 offset:54272
	s_nop 0
	s_mov_b32 m0, s44
	s_nop 0
	buffer_load_dwordx4 v134, s[12:15], s56 offen lds
	ds_read_b128 v[194:197], v137 offset:55296
	ds_read_b128 v[198:201], v137 offset:56320
	s_nop 0
	s_mov_b32 m0, s45
	s_nop 0
	buffer_load_dwordx4 v135, s[12:15], s56 offen lds
	s_nop 0
	s_mov_b32 m0, s42
	s_nop 0
	buffer_load_dwordx4 v134, s[16:19], s55 offen lds
	s_nop 0
	s_mov_b32 m0, s43
	s_nop 0
	buffer_load_dwordx4 v135, s[16:19], s55 offen lds
	s_waitcnt vmcnt(8)
	s_waitcnt lgkmcnt(0)
	s_setprio 1
	s_barrier
	v_mfma_f32_16x16x32_bf16 v[62:65], v[138:141], v[170:173], v[62:65]
	v_mfma_f32_16x16x32_bf16 v[58:61], v[146:149], v[170:173], v[58:61]
	v_mfma_f32_16x16x32_bf16 v[54:57], v[138:141], v[178:181], v[54:57]
	v_mfma_f32_16x16x32_bf16 v[42:45], v[146:149], v[178:181], v[42:45]
	v_mfma_f32_16x16x32_bf16 v[38:41], v[138:141], v[186:189], v[38:41]
	v_mfma_f32_16x16x32_bf16 v[26:29], v[146:149], v[186:189], v[26:29]
	v_mfma_f32_16x16x32_bf16 v[18:21], v[138:141], v[194:197], v[18:21]
	v_mfma_f32_16x16x32_bf16 v[10:13], v[146:149], v[194:197], v[10:13]
	v_mfma_f32_16x16x32_bf16 v[62:65], v[142:145], v[174:177], v[62:65]
	v_mfma_f32_16x16x32_bf16 v[58:61], v[150:153], v[174:177], v[58:61]
	v_mfma_f32_16x16x32_bf16 v[54:57], v[142:145], v[182:185], v[54:57]
	v_mfma_f32_16x16x32_bf16 v[42:45], v[150:153], v[182:185], v[42:45]
	v_mfma_f32_16x16x32_bf16 v[38:41], v[142:145], v[190:193], v[38:41]
	v_mfma_f32_16x16x32_bf16 v[26:29], v[150:153], v[190:193], v[26:29]
	v_mfma_f32_16x16x32_bf16 v[18:21], v[142:145], v[198:201], v[18:21]
	v_mfma_f32_16x16x32_bf16 v[10:13], v[150:153], v[198:201], v[10:13]
	s_setprio 0
	s_setprio 1
	v_mfma_f32_16x16x32_bf16 v[50:53], v[154:157], v[170:173], v[50:53]
	v_mfma_f32_16x16x32_bf16 v[46:49], v[162:165], v[170:173], v[46:49]
	v_mfma_f32_16x16x32_bf16 v[34:37], v[154:157], v[178:181], v[34:37]
	v_mfma_f32_16x16x32_bf16 v[30:33], v[162:165], v[178:181], v[30:33]
	v_mfma_f32_16x16x32_bf16 v[22:25], v[154:157], v[186:189], v[22:25]
	v_mfma_f32_16x16x32_bf16 v[14:17], v[162:165], v[186:189], v[14:17]
	v_mfma_f32_16x16x32_bf16 v[6:9], v[154:157], v[194:197], v[6:9]
	v_mfma_f32_16x16x32_bf16 v[2:5], v[162:165], v[194:197], v[2:5]
	v_mfma_f32_16x16x32_bf16 v[50:53], v[158:161], v[174:177], v[50:53]
	v_mfma_f32_16x16x32_bf16 v[46:49], v[166:169], v[174:177], v[46:49]
	v_mfma_f32_16x16x32_bf16 v[34:37], v[158:161], v[182:185], v[34:37]
	v_mfma_f32_16x16x32_bf16 v[30:33], v[166:169], v[182:185], v[30:33]
	v_mfma_f32_16x16x32_bf16 v[22:25], v[158:161], v[190:193], v[22:25]
	v_mfma_f32_16x16x32_bf16 v[14:17], v[166:169], v[190:193], v[14:17]
	v_mfma_f32_16x16x32_bf16 v[6:9], v[158:161], v[198:201], v[6:9]
	v_mfma_f32_16x16x32_bf16 v[2:5], v[166:169], v[198:201], v[2:5]
	s_barrier
	s_setprio 0
	s_add_i32 s2, s2, 2
	s_addk_i32 s3, 0x100
	s_cmp_gt_u32 s2, 41
	s_cbranch_scc0 .LBB0_1135
	s_andn2_b64 vcc, exec, s[4:5]
	s_cbranch_vccnz .LBB0_1123
	v_mov_b32_e32 v2, 0
	s_mov_b32 s20, s50
	s_mov_b32 s25, s51
	s_mov_b32 s30, s54
	s_mov_b32 s36, s53
	s_mov_b32 s49, s52
	v_mov_b32_e32 v3, v2
	v_mov_b32_e32 v4, v2
	v_mov_b32_e32 v5, v2
	v_mov_b32_e32 v6, v2
	v_mov_b32_e32 v7, v2
	v_mov_b32_e32 v8, v2
	v_mov_b32_e32 v9, v2
	v_mov_b32_e32 v14, v2
	v_mov_b32_e32 v15, v2
	v_mov_b32_e32 v16, v2
	v_mov_b32_e32 v17, v2
	v_mov_b32_e32 v22, v2
	v_mov_b32_e32 v23, v2
	v_mov_b32_e32 v24, v2
	v_mov_b32_e32 v25, v2
	v_mov_b32_e32 v30, v2
	v_mov_b32_e32 v31, v2
	v_mov_b32_e32 v32, v2
	v_mov_b32_e32 v33, v2
	v_mov_b32_e32 v34, v2
	v_mov_b32_e32 v35, v2
	v_mov_b32_e32 v36, v2
	v_mov_b32_e32 v37, v2
	v_mov_b32_e32 v46, v2
	v_mov_b32_e32 v47, v2
	v_mov_b32_e32 v48, v2
	v_mov_b32_e32 v49, v2
	v_mov_b32_e32 v50, v2
	v_mov_b32_e32 v51, v2
	v_mov_b32_e32 v52, v2
	v_mov_b32_e32 v53, v2
	v_mov_b32_e32 v10, v2
	v_mov_b32_e32 v11, v2
	v_mov_b32_e32 v12, v2
	v_mov_b32_e32 v13, v2
	v_mov_b32_e32 v18, v2
	v_mov_b32_e32 v19, v2
	v_mov_b32_e32 v20, v2
	v_mov_b32_e32 v21, v2
	v_mov_b32_e32 v26, v2
	v_mov_b32_e32 v27, v2
	v_mov_b32_e32 v28, v2
	v_mov_b32_e32 v29, v2
	v_mov_b32_e32 v38, v2
	v_mov_b32_e32 v39, v2
	v_mov_b32_e32 v40, v2
	v_mov_b32_e32 v41, v2
	v_mov_b32_e32 v42, v2
	v_mov_b32_e32 v43, v2
	v_mov_b32_e32 v44, v2
	v_mov_b32_e32 v45, v2
	v_mov_b32_e32 v54, v2
	v_mov_b32_e32 v55, v2
	v_mov_b32_e32 v56, v2
	v_mov_b32_e32 v57, v2
	v_mov_b32_e32 v58, v2
	v_mov_b32_e32 v59, v2
	v_mov_b32_e32 v60, v2
	v_mov_b32_e32 v61, v2
	v_mov_b32_e32 v62, v2
	v_mov_b32_e32 v63, v2
	v_mov_b32_e32 v64, v2
	v_mov_b32_e32 v65, v2
	v_mov_b32_e32 v66, v2
	v_mov_b32_e32 v67, v2
	v_mov_b32_e32 v68, v2
	v_mov_b32_e32 v69, v2
	v_mov_b32_e32 v70, v2
	v_mov_b32_e32 v71, v2
	v_mov_b32_e32 v72, v2
	v_mov_b32_e32 v73, v2
	v_mov_b32_e32 v78, v2
	v_mov_b32_e32 v79, v2
	v_mov_b32_e32 v80, v2
	v_mov_b32_e32 v81, v2
	v_mov_b32_e32 v82, v2
	v_mov_b32_e32 v83, v2
	v_mov_b32_e32 v84, v2
	v_mov_b32_e32 v85, v2
	v_mov_b32_e32 v94, v2
	v_mov_b32_e32 v95, v2
	v_mov_b32_e32 v96, v2
	v_mov_b32_e32 v97, v2
	v_mov_b32_e32 v98, v2
	v_mov_b32_e32 v99, v2
	v_mov_b32_e32 v100, v2
	v_mov_b32_e32 v101, v2
	v_mov_b32_e32 v110, v2
	v_mov_b32_e32 v111, v2
	v_mov_b32_e32 v112, v2
	v_mov_b32_e32 v113, v2
	v_mov_b32_e32 v114, v2
	v_mov_b32_e32 v115, v2
	v_mov_b32_e32 v116, v2
	v_mov_b32_e32 v117, v2
	v_mov_b32_e32 v74, v2
	v_mov_b32_e32 v75, v2
	v_mov_b32_e32 v76, v2
	v_mov_b32_e32 v77, v2
	v_mov_b32_e32 v86, v2
	v_mov_b32_e32 v87, v2
	v_mov_b32_e32 v88, v2
	v_mov_b32_e32 v89, v2
	v_mov_b32_e32 v90, v2
	v_mov_b32_e32 v91, v2
	v_mov_b32_e32 v92, v2
	v_mov_b32_e32 v93, v2
	v_mov_b32_e32 v102, v2
	v_mov_b32_e32 v103, v2
	v_mov_b32_e32 v104, v2
	v_mov_b32_e32 v105, v2
	v_mov_b32_e32 v106, v2
	v_mov_b32_e32 v107, v2
	v_mov_b32_e32 v108, v2
	v_mov_b32_e32 v109, v2
	v_mov_b32_e32 v118, v2
	v_mov_b32_e32 v119, v2
	v_mov_b32_e32 v120, v2
	v_mov_b32_e32 v121, v2
	v_mov_b32_e32 v122, v2
	v_mov_b32_e32 v123, v2
	v_mov_b32_e32 v124, v2
	v_mov_b32_e32 v125, v2
	v_mov_b32_e32 v126, v2
	v_mov_b32_e32 v127, v2
	v_mov_b32_e32 v128, v2
	v_mov_b32_e32 v129, v2
	s_branch .LBB0_1123
